# packed-vs-scalar fp32 (asm guide 7.5): the two v_pk_add_f32 between MFMAs in the attention loop split into scalar v_add_f32 pairs, on top of v32
# speedup vs baseline: 1.0033x; 1.0032x over previous
; __device__ __forceinline__ void finishSM(f32x16& p0, f32x16& p1, float alpha, float& l_reg, bf16x8& pa0, bf16x8& pa1, bf16x8& pa2, bf16x8& pa3) {
;   for (int r = 0; r < 16; ++r) p1[r] = __builtin_amdgcn_exp2f(p1[r]);
;   float ps = 0; for (int r = 0; r < 16; ++r) ps += p0[r]; for (int r = 0; r < 16; ++r) ps += p1[r];
;   { auto rr = __builtin_amdgcn_permlane32_swap(__float_as_uint(ps), __float_as_uint(ps), false, false);
;     ps = __uint_as_float(rr[0]) + __uint_as_float(rr[1]); }
;   l_reg = l_reg * alpha + ps;
;     ...
;   PK4(p0, 0, pa0); PK4(p0, 8, pa1); PK4(p1, 0, pa2); PK4(p1, 8, pa3);
;     ...
; }
.LBB0_352:
	s_waitcnt lgkmcnt(0)
	s_barrier
	ds_read_b128 v[80:83], v207 offset:16384
	ds_read_b128 v[84:87], v207 offset:24576
	ds_read_b128 v[162:165], v208 offset:16384
	ds_read_b128 v[166:169], v208 offset:24576
	v_exp_f32_e32 v170, v72
	v_exp_f32_e32 v171, v73
	v_exp_f32_e32 v172, v74
	v_exp_f32_e32 v173, v75
	v_exp_f32_e32 v174, v76
	v_exp_f32_e32 v175, v77
	v_exp_f32_e32 v176, v78
	v_exp_f32_e32 v79, v79
	s_waitcnt lgkmcnt(3)
	v_mfma_f32_32x32x16_bf16 v[96:111], v[80:83], v[142:145], 0
	v_exp_f32_e32 v236, v64
	v_add_f32_e32 v64, 0, v229
	v_add_f32_e32 v64, v243, v64
	v_add_f32_e32 v64, v244, v64
	s_waitcnt lgkmcnt(2)
	v_mfma_f32_32x32x16_bf16 v[80:95], v[84:87], v[142:145], 0
	v_add_f32_e32 v64, v246, v64
	v_add_f32_e32 v64, v242, v64
	v_add_f32_e32 v64, v245, v64
	s_waitcnt lgkmcnt(1)
	v_mfma_f32_32x32x16_bf16 v[96:111], v[162:165], v[138:141], v[96:111]
	v_add_f32_e32 v64, v227, v64
	v_add_f32_e32 v64, v228, v64
	v_add_f32_e32 v64, v223, v64
	s_waitcnt lgkmcnt(0)
	v_mfma_f32_32x32x16_bf16 v[80:95], v[166:169], v[138:141], v[80:95]
	ds_read_b128 v[162:165], v209 offset:16384
	ds_read_b128 v[166:169], v209 offset:24576
	v_add_f32_e32 v64, v226, v64
	v_add_f32_e32 v64, v224, v64
	v_add_f32_e32 v64, v225, v64
	v_add_f32_e32 v64, v220, v64
	v_exp_f32_e32 v237, v65
	s_waitcnt lgkmcnt(1)
	v_mfma_f32_32x32x16_bf16 v[96:111], v[162:165], v[112:115], v[96:111]
	v_add_f32_e32 v64, v222, v64
	v_exp_f32_e32 v238, v66
	v_add_f32_e32 v64, v219, v64
	v_exp_f32_e32 v239, v67
	s_waitcnt lgkmcnt(0)
	v_mfma_f32_32x32x16_bf16 v[80:95], v[166:169], v[112:115], v[80:95]
	ds_read_b128 v[162:165], v210 offset:16384
	ds_read_b128 v[166:169], v210 offset:24576
	v_add_f32_e32 v64, v221, v64
	v_exp_f32_e32 v247, v68
	v_add_f32_e32 v64, v236, v64
	v_exp_f32_e32 v248, v69
	s_waitcnt lgkmcnt(1)
	v_mfma_f32_32x32x16_bf16 v[96:111], v[162:165], v[116:119], v[96:111]
	v_add_f32_e32 v64, v237, v64
	v_exp_f32_e32 v249, v70
	v_add_f32_e32 v64, v238, v64
	v_exp_f32_e32 v252, v71
	s_waitcnt lgkmcnt(0)
	v_mfma_f32_32x32x16_bf16 v[80:95], v[166:169], v[116:119], v[80:95]
	ds_read_b128 v[162:165], v190 offset:16384
	ds_read_b128 v[166:169], v190 offset:24576
	v_add_f32_e32 v64, v239, v64
	v_add_f32_e32 v64, v247, v64
	v_add_f32_e32 v64, v248, v64
	v_add_f32_e32 v64, v249, v64
	v_add_f32_e32 v64, v252, v64
	v_add_f32_e32 v64, v170, v64
	s_waitcnt lgkmcnt(1)
	v_mfma_f32_32x32x16_bf16 v[96:111], v[162:165], v[120:123], v[96:111]
	v_add_f32_e32 v64, v171, v64
	v_add_f32_e32 v64, v172, v64
	v_add_f32_e32 v64, v173, v64
	v_add_f32_e32 v64, v174, v64
	v_add_f32_e32 v64, v175, v64
	s_waitcnt lgkmcnt(0)
	v_mfma_f32_32x32x16_bf16 v[80:95], v[166:169], v[120:123], v[80:95]
	ds_read_b128 v[162:165], v191 offset:16384
	ds_read_b128 v[166:169], v191 offset:24576
	v_add_f32_e32 v64, v176, v64
	v_add_f32_e32 v64, v79, v64
	v_mov_b32_e32 v65, v64
	s_nop 1
	v_permlane32_swap_b32_e32 v64, v65
	v_add_f32_e32 v64, v64, v65
	s_waitcnt lgkmcnt(1)
	v_mfma_f32_32x32x16_bf16 v[96:111], v[162:165], v[124:127], v[96:111]
	v_add_f32_e32 v128, v215, v64
	v_cvt_pk_bf16_f32 v64, v229, v243
	v_cvt_pk_bf16_f32 v65, v244, v246
	v_cvt_pk_bf16_f32 v66, v242, v245
	v_cvt_pk_bf16_f32 v67, v227, v228
	s_waitcnt lgkmcnt(0)
	v_mfma_f32_32x32x16_bf16 v[80:95], v[166:169], v[124:127], v[80:95]
	ds_read_b128 v[162:165], v192 offset:16384
	ds_read_b128 v[166:169], v192 offset:24576
	v_cvt_pk_bf16_f32 v68, v223, v226
	v_cvt_pk_bf16_f32 v69, v224, v225
	v_cvt_pk_bf16_f32 v70, v220, v222
	v_cvt_pk_bf16_f32 v71, v219, v221
	v_cvt_pk_bf16_f32 v72, v236, v237
	v_cvt_pk_bf16_f32 v73, v238, v239
	s_waitcnt lgkmcnt(1)
	v_mfma_f32_32x32x16_bf16 v[96:111], v[162:165], v[130:133], v[96:111]
	v_cvt_pk_bf16_f32 v74, v247, v248
	v_cvt_pk_bf16_f32 v75, v249, v252
	v_cvt_pk_bf16_f32 v76, v170, v171
	v_cvt_pk_bf16_f32 v77, v172, v173
	v_cvt_pk_bf16_f32 v78, v174, v175
	s_waitcnt lgkmcnt(0)
	v_mfma_f32_32x32x16_bf16 v[80:95], v[166:169], v[130:133], v[80:95]
	ds_read_b128 v[162:165], v193 offset:16384
	ds_read_b128 v[166:169], v193 offset:24576
	ds_read_b64_tr_b16 v[180:181], v206 offset:0
	ds_read_b64_tr_b16 v[182:183], v206 offset:0x800
	ds_read_b64_tr_b16 v[184:185], v206 offset:0x1000
	ds_read_b64_tr_b16 v[186:187], v206 offset:0x1800
	ds_read_b64_tr_b16 v[216:217], v206 offset:0x2000
	ds_read_b64_tr_b16 v[218:219], v206 offset:0x2800
	ds_read_b64_tr_b16 v[220:221], v206 offset:0x3000
	ds_read_b64_tr_b16 v[222:223], v206 offset:0x3800
	v_cvt_pk_bf16_f32 v79, v176, v79
	s_nop 0
	v_permlane32_swap_b32_e32 v64, v66
	v_permlane32_swap_b32_e32 v65, v67
	v_permlane32_swap_b32_e32 v68, v70
	v_permlane32_swap_b32_e32 v69, v71
	s_waitcnt lgkmcnt(9)
	v_mfma_f32_32x32x16_bf16 v[96:111], v[162:165], v[134:137], v[96:111]
	v_permlane32_swap_b32_e32 v72, v74
	v_permlane32_swap_b32_e32 v73, v75
	v_permlane32_swap_b32_e32 v76, v78
	v_permlane32_swap_b32_e32 v77, v79
	s_waitcnt lgkmcnt(8)
	v_mfma_f32_32x32x16_bf16 v[80:95], v[166:169], v[134:137], v[80:95]
	s_waitcnt vmcnt(0)
	ds_write_b128 v211, v[146:149] offset:32768
	s_nop 0
	s_waitcnt lgkmcnt(7)
	v_mfma_f32_32x32x16_bf16 v[0:15], v[64:67], v[180:183], v[0:15]
	ds_read_b64_tr_b16 v[180:181], v206 offset:0x200
	ds_read_b64_tr_b16 v[182:183], v206 offset:0xa00
	v_add_co_u32_e32 v166, vcc, s19, v178
	s_nop 1
	v_addc_co_u32_e32 v167, vcc, -1, v179, vcc
	v_add_co_u32_e32 v170, vcc, s20, v178
	s_nop 1
	v_addc_co_u32_e32 v171, vcc, -1, v179, vcc
	s_waitcnt lgkmcnt(7)
	v_mfma_f32_32x32x16_bf16 v[0:15], v[68:71], v[184:187], v[0:15]
	ds_read_b64_tr_b16 v[184:185], v206 offset:0x1200
	ds_read_b64_tr_b16 v[186:187], v206 offset:0x1a00
	global_load_dwordx4 v[162:165], v[166:167], off
	s_nop 0
	global_load_dwordx4 v[166:169], v[166:167], off offset:-512
	s_nop 0
	global_load_dwordx4 v[174:177], v[170:171], off
	s_nop 0
	global_load_dwordx4 v[170:173], v[170:171], off offset:-512
	s_waitcnt lgkmcnt(7)
; #define SBAR() __builtin_amdgcn_sched_barrier(0)
; template <int D0, int BOFF> __device__ __forceinline__ void pv_one_i(f32x16& od, int vb, bf16x8 pa0, bf16x8 pa1, bf16x8 pa2, bf16x8 pa3) {
;   const s16x4 l0 = tr_read<BOFF + v_rd_off(D0, 0, 0)>(vb), h0 = tr_read<BOFF + v_rd_off(D0, 0, 1)>(vb), l1 = tr_read<BOFF + v_rd_off(D0, 1, 0)>(vb), h1 = tr_read<BOFF + v_rd_off(D0, 1, 1)>(vb);
;   const s16x4 l2 = tr_read<BOFF + v_rd_off(D0, 2, 0)>(vb), h2 = tr_read<BOFF + v_rd_off(D0, 2, 1)>(vb), l3 = tr_read<BOFF + v_rd_off(D0, 3, 0)>(vb), h3 = tr_read<BOFF + v_rd_off(D0, 3, 1)>(vb);
;   asm volatile("s_waitcnt lgkmcnt(0)" ::: "memory"); SBAR();
;     ...
;   od = __builtin_amdgcn_mfma_f32_32x32x16_bf16(pa0, PK(l0, h0), od, 0, 0, 0);
;   od = __builtin_amdgcn_mfma_f32_32x32x16_bf16(pa1, PK(l1, h1), od, 0, 0, 0);
;   od = __builtin_amdgcn_mfma_f32_32x32x16_bf16(pa2, PK(l2, h2), od, 0, 0, 0);
;   od = __builtin_amdgcn_mfma_f32_32x32x16_bf16(pa3, PK(l3, h3), od, 0, 0, 0);
;     ...
; }
; template <int BOFF> __device__ __forceinline__ void pv_i(f32x16* o, int vb, bf16x8 pa0, bf16x8 pa1, bf16x8 pa2, bf16x8 pa3) {
;   pv_one_i<0, BOFF>(o[0], vb, pa0, pa1, pa2, pa3); pv_one_i<1, BOFF>(o[1], vb, pa0, pa1, pa2, pa3); pv_one_i<2, BOFF>(o[2], vb, pa0, pa1, pa2, pa3); pv_one_i<3, BOFF>(o[3], vb, pa0, pa1, pa2, pa3);
; }
	v_mfma_f32_32x32x16_bf16 v[0:15], v[72:75], v[216:219], v[0:15]
	ds_read_b64_tr_b16 v[216:217], v206 offset:0x2200
	ds_read_b64_tr_b16 v[218:219], v206 offset:0x2a00
	s_waitcnt lgkmcnt(7)
	v_mfma_f32_32x32x16_bf16 v[0:15], v[76:79], v[220:223], v[0:15]
	ds_read_b64_tr_b16 v[220:221], v206 offset:0x3200
	ds_read_b64_tr_b16 v[222:223], v206 offset:0x3a00
	ds_write_b128 v212, v[150:153] offset:32768
	s_waitcnt lgkmcnt(7)
	v_mfma_f32_32x32x16_bf16 v[16:31], v[64:67], v[180:183], v[16:31]
	ds_read_b64_tr_b16 v[180:181], v206 offset:0x400
	ds_read_b64_tr_b16 v[182:183], v206 offset:0xc00
	s_waitcnt lgkmcnt(7)
	v_mfma_f32_32x32x16_bf16 v[16:31], v[68:71], v[184:187], v[16:31]
	ds_read_b64_tr_b16 v[184:185], v206 offset:0x1400
	ds_read_b64_tr_b16 v[186:187], v206 offset:0x1c00
	s_waitcnt lgkmcnt(7)
	v_mfma_f32_32x32x16_bf16 v[16:31], v[72:75], v[216:219], v[16:31]
	ds_read_b64_tr_b16 v[216:217], v206 offset:0x2400
	ds_read_b64_tr_b16 v[218:219], v206 offset:0x2c00
	s_waitcnt lgkmcnt(7)
	v_mfma_f32_32x32x16_bf16 v[16:31], v[76:79], v[220:223], v[16:31]
	ds_read_b64_tr_b16 v[220:221], v206 offset:0x3400
	ds_read_b64_tr_b16 v[222:223], v206 offset:0x3c00
	ds_write_b128 v213, v[154:157] offset:32768
	s_waitcnt lgkmcnt(7)
	v_mfma_f32_32x32x16_bf16 v[32:47], v[64:67], v[180:183], v[32:47]
	ds_read_b64_tr_b16 v[180:181], v206 offset:0x600
	ds_read_b64_tr_b16 v[182:183], v206 offset:0xe00
	v_exp_f32_e32 v215, v108
	v_exp_f32_e32 v188, v102
	s_waitcnt lgkmcnt(7)
	v_mfma_f32_32x32x16_bf16 v[32:47], v[68:71], v[184:187], v[32:47]
	ds_read_b64_tr_b16 v[184:185], v206 offset:0x1600
	ds_read_b64_tr_b16 v[186:187], v206 offset:0x1e00
	v_exp_f32_e32 v189, v103
	v_exp_f32_e32 v196, v104
	s_waitcnt lgkmcnt(7)
	v_mfma_f32_32x32x16_bf16 v[32:47], v[72:75], v[216:219], v[32:47]
	ds_read_b64_tr_b16 v[216:217], v206 offset:0x2600
	ds_read_b64_tr_b16 v[218:219], v206 offset:0x2e00
	v_exp_f32_e32 v197, v105
	v_exp_f32_e32 v198, v106
	s_waitcnt lgkmcnt(7)
	v_mfma_f32_32x32x16_bf16 v[32:47], v[76:79], v[220:223], v[32:47]
	ds_read_b64_tr_b16 v[220:221], v206 offset:0x3600
	ds_read_b64_tr_b16 v[222:223], v206 offset:0x3e00
	v_exp_f32_e32 v199, v107
	ds_write_b128 v214, v[158:161] offset:32768
	s_waitcnt lgkmcnt(7)
	v_mfma_f32_32x32x16_bf16 v[48:63], v[64:67], v[180:183], v[48:63]
	s_waitcnt vmcnt(4)
	v_exp_f32_e32 v181, v96
	v_exp_f32_e32 v183, v97
	s_waitcnt lgkmcnt(5)
	v_mfma_f32_32x32x16_bf16 v[48:63], v[68:71], v[184:187], v[48:63]
	v_exp_f32_e32 v184, v98
	v_exp_f32_e32 v185, v99
	v_exp_f32_e32 v186, v100
	v_exp_f32_e32 v187, v101
	s_waitcnt lgkmcnt(3)
	v_mfma_f32_32x32x16_bf16 v[48:63], v[72:75], v[216:219], v[48:63]
	v_exp_f32_e32 v216, v109
	v_exp_f32_e32 v217, v110
	v_exp_f32_e32 v218, v111
	s_waitcnt lgkmcnt(0)
	s_barrier
	v_mfma_f32_32x32x16_bf16 v[48:63], v[76:79], v[220:223], v[48:63]
	ds_read_b128 v[64:67], v207 offset:32768
	ds_read_b128 v[96:99], v207 offset:40960
	ds_read_b128 v[146:149], v208 offset:32768
	ds_read_b128 v[150:153], v208 offset:40960
	v_exp_f32_e32 v154, v88
	v_exp_f32_e32 v155, v89
	v_exp_f32_e32 v156, v90
	v_exp_f32_e32 v157, v91
	v_exp_f32_e32 v158, v92
	v_exp_f32_e32 v159, v93
	v_exp_f32_e32 v160, v94
	v_exp_f32_e32 v95, v95
	s_waitcnt lgkmcnt(3)
	v_mfma_f32_32x32x16_bf16 v[64:79], v[64:67], v[142:145], 0
	v_exp_f32_e32 v236, v80
	v_add_f32_e32 v80, 0, v181
	v_add_f32_e32 v80, v183, v80
	v_add_f32_e32 v80, v184, v80
	s_waitcnt lgkmcnt(2)
	v_mfma_f32_32x32x16_bf16 v[96:111], v[96:99], v[142:145], 0
	v_add_f32_e32 v80, v185, v80
	v_add_f32_e32 v80, v186, v80
	v_add_f32_e32 v80, v187, v80
	s_waitcnt lgkmcnt(1)
	v_mfma_f32_32x32x16_bf16 v[64:79], v[146:149], v[138:141], v[64:79]
	v_add_f32_e32 v80, v188, v80
	v_add_f32_e32 v80, v189, v80
	v_add_f32_e32 v80, v196, v80
	s_waitcnt lgkmcnt(0)
	v_mfma_f32_32x32x16_bf16 v[96:111], v[150:153], v[138:141], v[96:111]
	ds_read_b128 v[146:149], v209 offset:32768
	ds_read_b128 v[150:153], v209 offset:40960
	v_add_f32_e32 v80, v197, v80
	v_add_f32_e32 v80, v198, v80
	v_add_f32_e32 v80, v199, v80
	v_add_f32_e32 v80, v215, v80
	v_exp_f32_e32 v237, v81
	s_waitcnt lgkmcnt(1)
	v_mfma_f32_32x32x16_bf16 v[64:79], v[146:149], v[112:115], v[64:79]
	v_add_f32_e32 v80, v216, v80
	v_exp_f32_e32 v238, v82
	v_add_f32_e32 v80, v217, v80
	v_exp_f32_e32 v239, v83
	s_waitcnt lgkmcnt(0)
	v_mfma_f32_32x32x16_bf16 v[96:111], v[150:153], v[112:115], v[96:111]
	ds_read_b128 v[146:149], v210 offset:32768
	ds_read_b128 v[150:153], v210 offset:40960
	v_add_f32_e32 v80, v218, v80
	v_exp_f32_e32 v247, v84
	v_add_f32_e32 v80, v236, v80
	v_exp_f32_e32 v248, v85
	s_waitcnt lgkmcnt(1)
	v_mfma_f32_32x32x16_bf16 v[64:79], v[146:149], v[116:119], v[64:79]
	v_add_f32_e32 v80, v237, v80
	v_exp_f32_e32 v249, v86
	v_add_f32_e32 v80, v238, v80
	v_exp_f32_e32 v252, v87
	s_waitcnt lgkmcnt(0)
	v_mfma_f32_32x32x16_bf16 v[96:111], v[150:153], v[116:119], v[96:111]
	ds_read_b128 v[146:149], v190 offset:32768
	ds_read_b128 v[150:153], v190 offset:40960
	v_add_f32_e32 v80, v239, v80
	v_add_f32_e32 v80, v247, v80
	v_add_f32_e32 v80, v248, v80
	v_add_f32_e32 v80, v249, v80
	v_add_f32_e32 v80, v252, v80
	v_add_f32_e32 v80, v154, v80
	s_waitcnt lgkmcnt(1)
	v_mfma_f32_32x32x16_bf16 v[64:79], v[146:149], v[120:123], v[64:79]
	v_add_f32_e32 v80, v155, v80
	v_add_f32_e32 v80, v156, v80
	v_add_f32_e32 v80, v157, v80
	v_add_f32_e32 v80, v158, v80
	v_add_f32_e32 v80, v159, v80
	s_waitcnt lgkmcnt(0)
	v_mfma_f32_32x32x16_bf16 v[96:111], v[150:153], v[120:123], v[96:111]
	ds_read_b128 v[146:149], v191 offset:32768
	ds_read_b128 v[150:153], v191 offset:40960
	v_add_f32_e32 v80, v160, v80
	v_add_f32_e32 v180, v95, v80
	v_mov_b32_e32 v182, v180
	v_cvt_pk_bf16_f32 v80, v181, v183
	v_cvt_pk_bf16_f32 v81, v184, v185
	v_cvt_pk_bf16_f32 v82, v186, v187
	s_waitcnt lgkmcnt(1)
; #define SBAR() __builtin_amdgcn_sched_barrier(0)
; template <int D0, int BOFF> __device__ __forceinline__ void pv_one_i(f32x16& od, int vb, bf16x8 pa0, bf16x8 pa1, bf16x8 pa2, bf16x8 pa3) {
;   const s16x4 l0 = tr_read<BOFF + v_rd_off(D0, 0, 0)>(vb), h0 = tr_read<BOFF + v_rd_off(D0, 0, 1)>(vb), l1 = tr_read<BOFF + v_rd_off(D0, 1, 0)>(vb), h1 = tr_read<BOFF + v_rd_off(D0, 1, 1)>(vb);
;   const s16x4 l2 = tr_read<BOFF + v_rd_off(D0, 2, 0)>(vb), h2 = tr_read<BOFF + v_rd_off(D0, 2, 1)>(vb), l3 = tr_read<BOFF + v_rd_off(D0, 3, 0)>(vb), h3 = tr_read<BOFF + v_rd_off(D0, 3, 1)>(vb);
;   asm volatile("s_waitcnt lgkmcnt(0)" ::: "memory"); SBAR();
;     ...
;   od = __builtin_amdgcn_mfma_f32_32x32x16_bf16(pa0, PK(l0, h0), od, 0, 0, 0);
;   od = __builtin_amdgcn_mfma_f32_32x32x16_bf16(pa1, PK(l1, h1), od, 0, 0, 0);
;   od = __builtin_amdgcn_mfma_f32_32x32x16_bf16(pa2, PK(l2, h2), od, 0, 0, 0);
;   od = __builtin_amdgcn_mfma_f32_32x32x16_bf16(pa3, PK(l3, h3), od, 0, 0, 0);
;     ...
; }
; template <int BOFF> __device__ __forceinline__ void pv_i(f32x16* o, int vb, bf16x8 pa0, bf16x8 pa1, bf16x8 pa2, bf16x8 pa3) {
;   pv_one_i<0, BOFF>(o[0], vb, pa0, pa1, pa2, pa3); pv_one_i<1, BOFF>(o[1], vb, pa0, pa1, pa2, pa3); pv_one_i<2, BOFF>(o[2], vb, pa0, pa1, pa2, pa3); pv_one_i<3, BOFF>(o[3], vb, pa0, pa1, pa2, pa3);
; }
	v_mfma_f32_32x32x16_bf16 v[64:79], v[146:149], v[124:127], v[64:79]
	v_cvt_pk_bf16_f32 v83, v188, v189
	v_cvt_pk_bf16_f32 v84, v196, v197
	v_cvt_pk_bf16_f32 v85, v198, v199
	v_cvt_pk_bf16_f32 v86, v215, v216
	v_cvt_pk_bf16_f32 v87, v217, v218
	s_waitcnt lgkmcnt(0)
	v_mfma_f32_32x32x16_bf16 v[96:111], v[150:153], v[124:127], v[96:111]
	ds_read_b128 v[146:149], v192 offset:32768
	ds_read_b128 v[150:153], v192 offset:40960
	v_cvt_pk_bf16_f32 v88, v236, v237
	v_cvt_pk_bf16_f32 v89, v238, v239
	v_cvt_pk_bf16_f32 v90, v247, v248
	v_cvt_pk_bf16_f32 v91, v249, v252
	v_cvt_pk_bf16_f32 v92, v154, v155
	v_cvt_pk_bf16_f32 v93, v156, v157
	s_waitcnt lgkmcnt(1)
	v_mfma_f32_32x32x16_bf16 v[64:79], v[146:149], v[130:133], v[64:79]
	v_cvt_pk_bf16_f32 v94, v158, v159
	v_cvt_pk_bf16_f32 v95, v160, v95
	s_nop 1
	v_permlane32_swap_b32_e32 v180, v182
	v_permlane32_swap_b32_e32 v80, v82
	s_waitcnt lgkmcnt(0)
	v_mfma_f32_32x32x16_bf16 v[96:111], v[150:153], v[130:133], v[96:111]
	ds_read_b128 v[146:149], v193 offset:32768
	ds_read_b128 v[150:153], v193 offset:40960
	ds_read_b64_tr_b16 v[184:185], v206 offset:0x4000
	ds_read_b64_tr_b16 v[186:187], v206 offset:0x4800
	ds_read_b64_tr_b16 v[216:217], v206 offset:0x5000
	ds_read_b64_tr_b16 v[218:219], v206 offset:0x5800
	ds_read_b64_tr_b16 v[220:221], v206 offset:0x6000
	ds_read_b64_tr_b16 v[222:223], v206 offset:0x6800
	ds_read_b64_tr_b16 v[224:225], v206 offset:0x7000
	ds_read_b64_tr_b16 v[226:227], v206 offset:0x7800
	v_permlane32_swap_b32_e32 v81, v83
	v_permlane32_swap_b32_e32 v84, v86
	v_permlane32_swap_b32_e32 v85, v87
	v_permlane32_swap_b32_e32 v88, v90
	v_permlane32_swap_b32_e32 v89, v91
	v_permlane32_swap_b32_e32 v92, v94
	s_waitcnt lgkmcnt(9)
	v_mfma_f32_32x32x16_bf16 v[64:79], v[146:149], v[134:137], v[64:79]
	v_permlane32_swap_b32_e32 v93, v95
	s_waitcnt lgkmcnt(8)
	v_mfma_f32_32x32x16_bf16 v[96:111], v[150:153], v[134:137], v[96:111]
	s_waitcnt vmcnt(0)
	ds_write_b128 v211, v[162:165]
	s_nop 0
	s_waitcnt lgkmcnt(7)
	v_mfma_f32_32x32x16_bf16 v[0:15], v[80:83], v[184:187], v[0:15]
	ds_read_b64_tr_b16 v[184:185], v206 offset:0x4200
	ds_read_b64_tr_b16 v[186:187], v206 offset:0x4a00
	v_add_co_u32_e32 v150, vcc, s21, v178
	s_nop 1
	v_addc_co_u32_e32 v151, vcc, -1, v179, vcc
	v_add_co_u32_e32 v154, vcc, s22, v178
	s_nop 1
	v_addc_co_u32_e32 v155, vcc, -1, v179, vcc
	s_waitcnt lgkmcnt(7)
	v_mfma_f32_32x32x16_bf16 v[0:15], v[84:87], v[216:219], v[0:15]
	ds_read_b64_tr_b16 v[216:217], v206 offset:0x5200
	ds_read_b64_tr_b16 v[218:219], v206 offset:0x5a00
	global_load_dwordx4 v[146:149], v[150:151], off
	s_nop 0
	global_load_dwordx4 v[150:153], v[150:151], off offset:-512
	s_nop 0
	global_load_dwordx4 v[158:161], v[154:155], off
	s_nop 0
	global_load_dwordx4 v[154:157], v[154:155], off offset:-512
	s_waitcnt lgkmcnt(7)
	v_mfma_f32_32x32x16_bf16 v[0:15], v[88:91], v[220:223], v[0:15]
	ds_read_b64_tr_b16 v[220:221], v206 offset:0x6200
	ds_read_b64_tr_b16 v[222:223], v206 offset:0x6a00
	s_waitcnt lgkmcnt(7)
	v_mfma_f32_32x32x16_bf16 v[0:15], v[92:95], v[224:227], v[0:15]
	ds_read_b64_tr_b16 v[224:225], v206 offset:0x7200
	ds_read_b64_tr_b16 v[226:227], v206 offset:0x7a00
	ds_write_b128 v212, v[174:177]
	s_waitcnt lgkmcnt(7)
	v_mfma_f32_32x32x16_bf16 v[16:31], v[80:83], v[184:187], v[16:31]
	ds_read_b64_tr_b16 v[184:185], v206 offset:0x4400
	ds_read_b64_tr_b16 v[186:187], v206 offset:0x4c00
	s_waitcnt lgkmcnt(7)
	v_mfma_f32_32x32x16_bf16 v[16:31], v[84:87], v[216:219], v[16:31]
	ds_read_b64_tr_b16 v[216:217], v206 offset:0x5400
	ds_read_b64_tr_b16 v[218:219], v206 offset:0x5c00
	s_waitcnt lgkmcnt(7)
	v_mfma_f32_32x32x16_bf16 v[16:31], v[88:91], v[220:223], v[16:31]
	ds_read_b64_tr_b16 v[220:221], v206 offset:0x6400
	ds_read_b64_tr_b16 v[222:223], v206 offset:0x6c00
	s_waitcnt lgkmcnt(7)
	v_mfma_f32_32x32x16_bf16 v[16:31], v[92:95], v[224:227], v[16:31]
	ds_read_b64_tr_b16 v[224:225], v206 offset:0x7400
	ds_read_b64_tr_b16 v[226:227], v206 offset:0x7c00
	ds_write_b128 v213, v[166:169]
	s_waitcnt lgkmcnt(7)
	v_mfma_f32_32x32x16_bf16 v[32:47], v[80:83], v[184:187], v[32:47]
	ds_read_b64_tr_b16 v[184:185], v206 offset:0x4600
	ds_read_b64_tr_b16 v[186:187], v206 offset:0x4e00
	v_exp_f32_e32 v215, v74
	v_exp_f32_e32 v188, v68
	s_waitcnt lgkmcnt(7)
	v_mfma_f32_32x32x16_bf16 v[32:47], v[84:87], v[216:219], v[32:47]
	ds_read_b64_tr_b16 v[216:217], v206 offset:0x5600
	ds_read_b64_tr_b16 v[218:219], v206 offset:0x5e00
	v_exp_f32_e32 v189, v69
	v_exp_f32_e32 v196, v70
	s_waitcnt lgkmcnt(7)
	v_mfma_f32_32x32x16_bf16 v[32:47], v[88:91], v[220:223], v[32:47]
	ds_read_b64_tr_b16 v[220:221], v206 offset:0x6600
	ds_read_b64_tr_b16 v[222:223], v206 offset:0x6e00
	v_exp_f32_e32 v197, v71
	v_exp_f32_e32 v198, v72
	s_waitcnt lgkmcnt(7)
	v_mfma_f32_32x32x16_bf16 v[32:47], v[92:95], v[224:227], v[32:47]
	ds_read_b64_tr_b16 v[224:225], v206 offset:0x7600
	ds_read_b64_tr_b16 v[226:227], v206 offset:0x7e00
	v_exp_f32_e32 v199, v73
	ds_write_b128 v214, v[170:173]
	s_waitcnt lgkmcnt(7)
	v_mfma_f32_32x32x16_bf16 v[48:63], v[80:83], v[184:187], v[48:63]
	s_waitcnt vmcnt(4)
	v_exp_f32_e32 v184, v64
	v_exp_f32_e32 v185, v65
	v_exp_f32_e32 v186, v66
	v_exp_f32_e32 v187, v67
	s_waitcnt lgkmcnt(5)
	v_mfma_f32_32x32x16_bf16 v[48:63], v[84:87], v[216:219], v[48:63]
	v_exp_f32_e32 v219, v78
	v_exp_f32_e32 v216, v75
	s_waitcnt lgkmcnt(3)
	v_mfma_f32_32x32x16_bf16 v[48:63], v[88:91], v[220:223], v[48:63]
	v_exp_f32_e32 v220, v79
	v_exp_f32_e32 v217, v76
	v_exp_f32_e32 v218, v77
	s_waitcnt lgkmcnt(0)
	s_barrier
; __device__ __forceinline__ void finishSM(f32x16& p0, f32x16& p1, float alpha, float& l_reg, bf16x8& pa0, bf16x8& pa1, bf16x8& pa2, bf16x8& pa3) {
;   for (int r = 0; r < 16; ++r) p1[r] = __builtin_amdgcn_exp2f(p1[r]);
;   float ps = 0; for (int r = 0; r < 16; ++r) ps += p0[r]; for (int r = 0; r < 16; ++r) ps += p1[r];
;   { auto rr = __builtin_amdgcn_permlane32_swap(__float_as_uint(ps), __float_as_uint(ps), false, false);
;     ps = __uint_as_float(rr[0]) + __uint_as_float(rr[1]); }
;   l_reg = l_reg * alpha + ps;
;     ...
;   PK4(p0, 0, pa0); PK4(p0, 8, pa1); PK4(p1, 0, pa2); PK4(p1, 8, pa3);
;     ...
; }
	v_mfma_f32_32x32x16_bf16 v[48:63], v[92:95], v[224:227], v[48:63]
	ds_read_b128 v[64:67], v207
	ds_read_b128 v[68:71], v207 offset:8192
	ds_read_b128 v[162:165], v208
	ds_read_b128 v[166:169], v208 offset:8192
	v_exp_f32_e32 v170, v104
	v_exp_f32_e32 v171, v105
	v_exp_f32_e32 v172, v106
	v_exp_f32_e32 v173, v107
	v_exp_f32_e32 v174, v108
	v_exp_f32_e32 v175, v109
	v_exp_f32_e32 v176, v110
	v_exp_f32_e32 v111, v111
	s_waitcnt lgkmcnt(3)
	v_mfma_f32_32x32x16_bf16 v[80:95], v[64:67], v[142:145], 0
	v_exp_f32_e32 v236, v96
	v_add_f32_e32 v96, 0, v184
	v_add_f32_e32 v96, v185, v96
	v_add_f32_e32 v96, v186, v96
	s_waitcnt lgkmcnt(2)
	v_mfma_f32_32x32x16_bf16 v[64:79], v[68:71], v[142:145], 0
	v_add_f32_e32 v96, v187, v96
	v_add_f32_e32 v96, v188, v96
	v_add_f32_e32 v96, v189, v96
	s_waitcnt lgkmcnt(1)
	v_mfma_f32_32x32x16_bf16 v[80:95], v[162:165], v[138:141], v[80:95]
	v_add_f32_e32 v96, v196, v96
	v_add_f32_e32 v96, v197, v96
	v_add_f32_e32 v96, v198, v96
	s_waitcnt lgkmcnt(0)
	v_mfma_f32_32x32x16_bf16 v[64:79], v[166:169], v[138:141], v[64:79]
	ds_read_b128 v[162:165], v209
	ds_read_b128 v[166:169], v209 offset:8192
	v_add_f32_e32 v96, v199, v96
	v_add_f32_e32 v96, v215, v96
	v_add_f32_e32 v96, v216, v96
	v_add_f32_e32 v96, v217, v96
	v_exp_f32_e32 v237, v97
	s_waitcnt lgkmcnt(1)
	v_mfma_f32_32x32x16_bf16 v[80:95], v[162:165], v[112:115], v[80:95]
	v_add_f32_e32 v96, v218, v96
	v_exp_f32_e32 v238, v98
	v_add_f32_e32 v96, v219, v96
	v_exp_f32_e32 v239, v99
	s_waitcnt lgkmcnt(0)
	v_mfma_f32_32x32x16_bf16 v[64:79], v[166:169], v[112:115], v[64:79]
	ds_read_b128 v[162:165], v210
	ds_read_b128 v[166:169], v210 offset:8192
	v_add_f32_e32 v96, v220, v96
	v_exp_f32_e32 v247, v100
	v_add_f32_e32 v96, v236, v96
	v_exp_f32_e32 v248, v101
	s_waitcnt lgkmcnt(1)
	v_mfma_f32_32x32x16_bf16 v[80:95], v[162:165], v[116:119], v[80:95]
	v_add_f32_e32 v96, v237, v96
	v_exp_f32_e32 v249, v102
	v_add_f32_e32 v96, v238, v96
	v_exp_f32_e32 v252, v103
	s_waitcnt lgkmcnt(0)
	v_mfma_f32_32x32x16_bf16 v[64:79], v[166:169], v[116:119], v[64:79]
	ds_read_b128 v[162:165], v190 offset:0
	ds_read_b128 v[166:169], v190 offset:8192
	v_add_f32_e32 v96, v239, v96
	v_add_f32_e32 v96, v247, v96
	v_add_f32_e32 v96, v248, v96
	v_add_f32_e32 v96, v249, v96
	v_add_f32_e32 v96, v252, v96
	v_add_f32_e32 v96, v170, v96
	s_waitcnt lgkmcnt(1)
	v_mfma_f32_32x32x16_bf16 v[80:95], v[162:165], v[120:123], v[80:95]
	v_add_f32_e32 v96, v171, v96
	v_add_f32_e32 v96, v172, v96
	v_add_f32_e32 v96, v173, v96
	v_add_f32_e32 v96, v174, v96
	v_add_f32_e32 v96, v175, v96
	s_waitcnt lgkmcnt(0)
	v_mfma_f32_32x32x16_bf16 v[64:79], v[166:169], v[120:123], v[64:79]
	ds_read_b128 v[162:165], v191 offset:0
	ds_read_b128 v[166:169], v191 offset:8192
	v_add_f32_e32 v96, v176, v96
	v_add_f32_e32 v181, v111, v96
	v_mov_b32_e32 v183, v181
	s_nop 1
	v_permlane32_swap_b32_e32 v181, v183
	v_add_f32_e32 v96, v180, v182
	v_add_f32_e32 v97, v181, v183
	s_waitcnt lgkmcnt(1)
	v_mfma_f32_32x32x16_bf16 v[80:95], v[162:165], v[124:127], v[80:95]
	s_nop 0
	v_add_f32_e32 v96, v128, v96
	v_add_f32_e32 v128, v96, v97
	v_cvt_pk_bf16_f32 v96, v184, v185
	v_cvt_pk_bf16_f32 v97, v186, v187
	s_waitcnt lgkmcnt(0)
	v_mfma_f32_32x32x16_bf16 v[64:79], v[166:169], v[124:127], v[64:79]
	ds_read_b128 v[162:165], v192 offset:0
	ds_read_b128 v[166:169], v192 offset:8192
	v_cvt_pk_bf16_f32 v98, v188, v189
	v_cvt_pk_bf16_f32 v99, v196, v197
	v_cvt_pk_bf16_f32 v100, v198, v199
	v_cvt_pk_bf16_f32 v101, v215, v216
	v_cvt_pk_bf16_f32 v102, v217, v218
	v_cvt_pk_bf16_f32 v103, v219, v220
	s_waitcnt lgkmcnt(1)
	v_mfma_f32_32x32x16_bf16 v[80:95], v[162:165], v[130:133], v[80:95]
	v_cvt_pk_bf16_f32 v104, v236, v237
	v_cvt_pk_bf16_f32 v105, v238, v239
	v_cvt_pk_bf16_f32 v106, v247, v248
	v_cvt_pk_bf16_f32 v107, v249, v252
	v_cvt_pk_bf16_f32 v108, v170, v171
	s_waitcnt lgkmcnt(0)
	v_mfma_f32_32x32x16_bf16 v[64:79], v[166:169], v[130:133], v[64:79]
	ds_read_b128 v[162:165], v193 offset:0
	ds_read_b128 v[166:169], v193 offset:8192
	ds_read_b64_tr_b16 v[180:181], v206 offset:0x8000
	ds_read_b64_tr_b16 v[182:183], v206 offset:0x8800
	ds_read_b64_tr_b16 v[184:185], v206 offset:0x9000
	ds_read_b64_tr_b16 v[186:187], v206 offset:0x9800
	ds_read_b64_tr_b16 v[216:217], v206 offset:0xa000
	ds_read_b64_tr_b16 v[218:219], v206 offset:0xa800
	ds_read_b64_tr_b16 v[220:221], v206 offset:0xb000
	ds_read_b64_tr_b16 v[222:223], v206 offset:0xb800
	v_cvt_pk_bf16_f32 v109, v172, v173
	v_cvt_pk_bf16_f32 v110, v174, v175
	v_cvt_pk_bf16_f32 v111, v176, v111
	s_nop 0
	v_permlane32_swap_b32_e32 v96, v98
	v_permlane32_swap_b32_e32 v97, v99
	s_waitcnt lgkmcnt(9)
	v_mfma_f32_32x32x16_bf16 v[80:95], v[162:165], v[134:137], v[80:95]
	v_permlane32_swap_b32_e32 v100, v102
	v_permlane32_swap_b32_e32 v101, v103
	v_permlane32_swap_b32_e32 v104, v106
	v_permlane32_swap_b32_e32 v105, v107
	v_permlane32_swap_b32_e32 v108, v110
	s_waitcnt lgkmcnt(8)
	v_mfma_f32_32x32x16_bf16 v[64:79], v[166:169], v[134:137], v[64:79]
	v_permlane32_swap_b32_e32 v109, v111
	s_waitcnt vmcnt(0)
	ds_write_b128 v211, v[146:149] offset:16384
	s_nop 0
	s_waitcnt lgkmcnt(7)
	v_mfma_f32_32x32x16_bf16 v[0:15], v[96:99], v[180:183], v[0:15]
	ds_read_b64_tr_b16 v[180:181], v206 offset:0x8200
	ds_read_b64_tr_b16 v[182:183], v206 offset:0x8a00
	v_add_co_u32_e32 v166, vcc, s23, v178
	s_nop 1
	v_addc_co_u32_e32 v167, vcc, -1, v179, vcc
	v_add_co_u32_e32 v170, vcc, s24, v178
	s_nop 1
	v_addc_co_u32_e32 v171, vcc, -1, v179, vcc
	s_waitcnt lgkmcnt(7)
; #define SBAR() __builtin_amdgcn_sched_barrier(0)
; template <int D0, int BOFF> __device__ __forceinline__ void pv_one_i(f32x16& od, int vb, bf16x8 pa0, bf16x8 pa1, bf16x8 pa2, bf16x8 pa3) {
;   const s16x4 l0 = tr_read<BOFF + v_rd_off(D0, 0, 0)>(vb), h0 = tr_read<BOFF + v_rd_off(D0, 0, 1)>(vb), l1 = tr_read<BOFF + v_rd_off(D0, 1, 0)>(vb), h1 = tr_read<BOFF + v_rd_off(D0, 1, 1)>(vb);
;   const s16x4 l2 = tr_read<BOFF + v_rd_off(D0, 2, 0)>(vb), h2 = tr_read<BOFF + v_rd_off(D0, 2, 1)>(vb), l3 = tr_read<BOFF + v_rd_off(D0, 3, 0)>(vb), h3 = tr_read<BOFF + v_rd_off(D0, 3, 1)>(vb);
;   asm volatile("s_waitcnt lgkmcnt(0)" ::: "memory"); SBAR();
;     ...
;   od = __builtin_amdgcn_mfma_f32_32x32x16_bf16(pa0, PK(l0, h0), od, 0, 0, 0);
;   od = __builtin_amdgcn_mfma_f32_32x32x16_bf16(pa1, PK(l1, h1), od, 0, 0, 0);
;   od = __builtin_amdgcn_mfma_f32_32x32x16_bf16(pa2, PK(l2, h2), od, 0, 0, 0);
;   od = __builtin_amdgcn_mfma_f32_32x32x16_bf16(pa3, PK(l3, h3), od, 0, 0, 0);
;     ...
; }
; template <int BOFF> __device__ __forceinline__ void pv_i(f32x16* o, int vb, bf16x8 pa0, bf16x8 pa1, bf16x8 pa2, bf16x8 pa3) {
;   pv_one_i<0, BOFF>(o[0], vb, pa0, pa1, pa2, pa3); pv_one_i<1, BOFF>(o[1], vb, pa0, pa1, pa2, pa3); pv_one_i<2, BOFF>(o[2], vb, pa0, pa1, pa2, pa3); pv_one_i<3, BOFF>(o[3], vb, pa0, pa1, pa2, pa3);
; }
	v_mfma_f32_32x32x16_bf16 v[0:15], v[100:103], v[184:187], v[0:15]
	ds_read_b64_tr_b16 v[184:185], v206 offset:0x9200
	ds_read_b64_tr_b16 v[186:187], v206 offset:0x9a00
	global_load_dwordx4 v[162:165], v[166:167], off
	s_nop 0
	global_load_dwordx4 v[166:169], v[166:167], off offset:-512
	s_nop 0
	global_load_dwordx4 v[174:177], v[170:171], off
	s_nop 0
	global_load_dwordx4 v[170:173], v[170:171], off offset:-512
	s_waitcnt lgkmcnt(7)
	v_mfma_f32_32x32x16_bf16 v[0:15], v[104:107], v[216:219], v[0:15]
	ds_read_b64_tr_b16 v[216:217], v206 offset:0xa200
	ds_read_b64_tr_b16 v[218:219], v206 offset:0xaa00
	s_waitcnt lgkmcnt(7)
	v_mfma_f32_32x32x16_bf16 v[0:15], v[108:111], v[220:223], v[0:15]
	ds_read_b64_tr_b16 v[220:221], v206 offset:0xb200
	ds_read_b64_tr_b16 v[222:223], v206 offset:0xba00
	ds_write_b128 v212, v[158:161] offset:16384
	s_waitcnt lgkmcnt(7)
	v_mfma_f32_32x32x16_bf16 v[16:31], v[96:99], v[180:183], v[16:31]
	ds_read_b64_tr_b16 v[180:181], v206 offset:0x8400
	ds_read_b64_tr_b16 v[182:183], v206 offset:0x8c00
	s_waitcnt lgkmcnt(7)
	v_mfma_f32_32x32x16_bf16 v[16:31], v[100:103], v[184:187], v[16:31]
	ds_read_b64_tr_b16 v[184:185], v206 offset:0x9400
	ds_read_b64_tr_b16 v[186:187], v206 offset:0x9c00
	s_waitcnt lgkmcnt(7)
	v_mfma_f32_32x32x16_bf16 v[16:31], v[104:107], v[216:219], v[16:31]
	ds_read_b64_tr_b16 v[216:217], v206 offset:0xa400
	ds_read_b64_tr_b16 v[218:219], v206 offset:0xac00
	s_waitcnt lgkmcnt(7)
	v_mfma_f32_32x32x16_bf16 v[16:31], v[108:111], v[220:223], v[16:31]
	ds_read_b64_tr_b16 v[220:221], v206 offset:0xb400
	ds_read_b64_tr_b16 v[222:223], v206 offset:0xbc00
	ds_write_b128 v213, v[150:153] offset:16384
	s_waitcnt lgkmcnt(7)
	v_mfma_f32_32x32x16_bf16 v[32:47], v[96:99], v[180:183], v[32:47]
	ds_read_b64_tr_b16 v[180:181], v206 offset:0x8600
	ds_read_b64_tr_b16 v[182:183], v206 offset:0x8e00
	v_exp_f32_e32 v215, v92
	v_exp_f32_e32 v188, v86
	s_waitcnt lgkmcnt(7)
	v_mfma_f32_32x32x16_bf16 v[32:47], v[100:103], v[184:187], v[32:47]
	ds_read_b64_tr_b16 v[184:185], v206 offset:0x9600
	ds_read_b64_tr_b16 v[186:187], v206 offset:0x9e00
	v_exp_f32_e32 v189, v87
	v_exp_f32_e32 v196, v88
	s_waitcnt lgkmcnt(7)
	v_mfma_f32_32x32x16_bf16 v[32:47], v[104:107], v[216:219], v[32:47]
	ds_read_b64_tr_b16 v[216:217], v206 offset:0xa600
	ds_read_b64_tr_b16 v[218:219], v206 offset:0xae00
	v_exp_f32_e32 v197, v89
	v_exp_f32_e32 v198, v90
	s_waitcnt lgkmcnt(7)
	v_mfma_f32_32x32x16_bf16 v[32:47], v[108:111], v[220:223], v[32:47]
	ds_read_b64_tr_b16 v[220:221], v206 offset:0xb600
	ds_read_b64_tr_b16 v[222:223], v206 offset:0xbe00
	v_exp_f32_e32 v199, v91
	ds_write_b128 v214, v[154:157] offset:16384
	s_waitcnt lgkmcnt(7)
	v_mfma_f32_32x32x16_bf16 v[48:63], v[96:99], v[180:183], v[48:63]
	s_waitcnt vmcnt(4)
	v_exp_f32_e32 v181, v80
	v_exp_f32_e32 v183, v81
	s_waitcnt lgkmcnt(5)
	v_mfma_f32_32x32x16_bf16 v[48:63], v[100:103], v[184:187], v[48:63]
	v_exp_f32_e32 v184, v82
	v_exp_f32_e32 v185, v83
	v_exp_f32_e32 v186, v84
	v_exp_f32_e32 v187, v85
	s_waitcnt lgkmcnt(3)
	v_mfma_f32_32x32x16_bf16 v[48:63], v[104:107], v[216:219], v[48:63]
	v_exp_f32_e32 v216, v93
	v_exp_f32_e32 v217, v94
	v_exp_f32_e32 v218, v95
	s_waitcnt lgkmcnt(0)
	s_barrier
	v_mfma_f32_32x32x16_bf16 v[48:63], v[108:111], v[220:223], v[48:63]
	ds_read_b128 v[80:83], v207 offset:16384
	ds_read_b128 v[96:99], v207 offset:24576
	ds_read_b128 v[146:149], v208 offset:16384
	ds_read_b128 v[150:153], v208 offset:24576
	v_exp_f32_e32 v154, v72
	v_exp_f32_e32 v155, v73
	v_exp_f32_e32 v156, v74
	v_exp_f32_e32 v157, v75
	v_exp_f32_e32 v158, v76
	v_exp_f32_e32 v159, v77
	v_exp_f32_e32 v160, v78
	v_exp_f32_e32 v79, v79
	s_waitcnt lgkmcnt(3)
	v_mfma_f32_32x32x16_bf16 v[80:95], v[80:83], v[142:145], 0
	v_exp_f32_e32 v236, v64
	v_add_f32_e32 v64, 0, v181
	v_add_f32_e32 v64, v183, v64
	v_add_f32_e32 v64, v184, v64
	s_waitcnt lgkmcnt(2)
	v_mfma_f32_32x32x16_bf16 v[96:111], v[96:99], v[142:145], 0
	v_add_f32_e32 v64, v185, v64
	v_add_f32_e32 v64, v186, v64
	v_add_f32_e32 v64, v187, v64
	s_waitcnt lgkmcnt(1)
	v_mfma_f32_32x32x16_bf16 v[80:95], v[146:149], v[138:141], v[80:95]
	v_add_f32_e32 v64, v188, v64
	v_add_f32_e32 v64, v189, v64
	v_add_f32_e32 v64, v196, v64
	s_waitcnt lgkmcnt(0)
	v_mfma_f32_32x32x16_bf16 v[96:111], v[150:153], v[138:141], v[96:111]
	ds_read_b128 v[146:149], v209 offset:16384
	ds_read_b128 v[150:153], v209 offset:24576
	v_add_f32_e32 v64, v197, v64
	v_add_f32_e32 v64, v198, v64
	v_add_f32_e32 v64, v199, v64
	v_add_f32_e32 v64, v215, v64
	v_exp_f32_e32 v237, v65
	s_waitcnt lgkmcnt(1)
	v_mfma_f32_32x32x16_bf16 v[80:95], v[146:149], v[112:115], v[80:95]
	v_add_f32_e32 v64, v216, v64
	v_exp_f32_e32 v238, v66
	v_add_f32_e32 v64, v217, v64
	v_exp_f32_e32 v239, v67
	s_waitcnt lgkmcnt(0)
	v_mfma_f32_32x32x16_bf16 v[96:111], v[150:153], v[112:115], v[96:111]
	ds_read_b128 v[146:149], v210 offset:16384
	ds_read_b128 v[150:153], v210 offset:24576
	v_add_f32_e32 v64, v218, v64
	v_exp_f32_e32 v247, v68
	v_add_f32_e32 v64, v236, v64
	v_exp_f32_e32 v248, v69
	s_waitcnt lgkmcnt(1)
	v_mfma_f32_32x32x16_bf16 v[80:95], v[146:149], v[116:119], v[80:95]
	v_add_f32_e32 v64, v237, v64
	v_exp_f32_e32 v249, v70
	v_add_f32_e32 v64, v238, v64
	v_exp_f32_e32 v252, v71
	s_waitcnt lgkmcnt(0)
	v_mfma_f32_32x32x16_bf16 v[96:111], v[150:153], v[116:119], v[96:111]
	ds_read_b128 v[146:149], v190 offset:16384
	ds_read_b128 v[150:153], v190 offset:24576
	v_add_f32_e32 v64, v239, v64
	v_add_f32_e32 v64, v247, v64
	v_add_f32_e32 v64, v248, v64
	v_add_f32_e32 v64, v249, v64
	v_add_f32_e32 v64, v252, v64
	v_add_f32_e32 v64, v154, v64
	s_waitcnt lgkmcnt(1)
; #define SBAR() __builtin_amdgcn_sched_barrier(0)
; template <int D0, int BOFF> __device__ __forceinline__ void pv_one_i(f32x16& od, int vb, bf16x8 pa0, bf16x8 pa1, bf16x8 pa2, bf16x8 pa3) {
;   const s16x4 l0 = tr_read<BOFF + v_rd_off(D0, 0, 0)>(vb), h0 = tr_read<BOFF + v_rd_off(D0, 0, 1)>(vb), l1 = tr_read<BOFF + v_rd_off(D0, 1, 0)>(vb), h1 = tr_read<BOFF + v_rd_off(D0, 1, 1)>(vb);
;   const s16x4 l2 = tr_read<BOFF + v_rd_off(D0, 2, 0)>(vb), h2 = tr_read<BOFF + v_rd_off(D0, 2, 1)>(vb), l3 = tr_read<BOFF + v_rd_off(D0, 3, 0)>(vb), h3 = tr_read<BOFF + v_rd_off(D0, 3, 1)>(vb);
;   asm volatile("s_waitcnt lgkmcnt(0)" ::: "memory"); SBAR();
;     ...
;   od = __builtin_amdgcn_mfma_f32_32x32x16_bf16(pa0, PK(l0, h0), od, 0, 0, 0);
;   od = __builtin_amdgcn_mfma_f32_32x32x16_bf16(pa1, PK(l1, h1), od, 0, 0, 0);
;   od = __builtin_amdgcn_mfma_f32_32x32x16_bf16(pa2, PK(l2, h2), od, 0, 0, 0);
;   od = __builtin_amdgcn_mfma_f32_32x32x16_bf16(pa3, PK(l3, h3), od, 0, 0, 0);
;     ...
; }
; template <int BOFF> __device__ __forceinline__ void pv_i(f32x16* o, int vb, bf16x8 pa0, bf16x8 pa1, bf16x8 pa2, bf16x8 pa3) {
;   pv_one_i<0, BOFF>(o[0], vb, pa0, pa1, pa2, pa3); pv_one_i<1, BOFF>(o[1], vb, pa0, pa1, pa2, pa3); pv_one_i<2, BOFF>(o[2], vb, pa0, pa1, pa2, pa3); pv_one_i<3, BOFF>(o[3], vb, pa0, pa1, pa2, pa3);
; }
	v_mfma_f32_32x32x16_bf16 v[80:95], v[146:149], v[120:123], v[80:95]
	v_add_f32_e32 v64, v155, v64
	v_add_f32_e32 v64, v156, v64
	v_add_f32_e32 v64, v157, v64
	v_add_f32_e32 v64, v158, v64
	v_add_f32_e32 v64, v159, v64
	s_waitcnt lgkmcnt(0)
	v_mfma_f32_32x32x16_bf16 v[96:111], v[150:153], v[120:123], v[96:111]
	ds_read_b128 v[146:149], v191 offset:16384
	ds_read_b128 v[150:153], v191 offset:24576
	v_add_f32_e32 v64, v160, v64
	v_add_f32_e32 v180, v79, v64
	v_cvt_pk_bf16_f32 v64, v181, v183
	v_cvt_pk_bf16_f32 v65, v184, v185
	v_cvt_pk_bf16_f32 v66, v186, v187
	v_cvt_pk_bf16_f32 v67, v188, v189
	s_waitcnt lgkmcnt(1)
	v_mfma_f32_32x32x16_bf16 v[80:95], v[146:149], v[124:127], v[80:95]
	v_cvt_pk_bf16_f32 v68, v196, v197
	v_cvt_pk_bf16_f32 v69, v198, v199
	v_cvt_pk_bf16_f32 v70, v215, v216
	v_cvt_pk_bf16_f32 v71, v217, v218
	v_cvt_pk_bf16_f32 v72, v236, v237
	s_waitcnt lgkmcnt(0)
	v_mfma_f32_32x32x16_bf16 v[96:111], v[150:153], v[124:127], v[96:111]
	ds_read_b128 v[146:149], v192 offset:16384
	ds_read_b128 v[150:153], v192 offset:24576
	v_cvt_pk_bf16_f32 v73, v238, v239
	v_cvt_pk_bf16_f32 v74, v247, v248
	v_cvt_pk_bf16_f32 v75, v249, v252
	v_cvt_pk_bf16_f32 v76, v154, v155
	v_cvt_pk_bf16_f32 v77, v156, v157
	v_cvt_pk_bf16_f32 v78, v158, v159
	s_waitcnt lgkmcnt(1)
	v_mfma_f32_32x32x16_bf16 v[80:95], v[146:149], v[130:133], v[80:95]
	v_cvt_pk_bf16_f32 v79, v160, v79
	v_mov_b32_e32 v182, v180
	v_permlane32_swap_b32_e32 v64, v66
	v_permlane32_swap_b32_e32 v65, v67
	v_permlane32_swap_b32_e32 v68, v70
	s_waitcnt lgkmcnt(0)
	v_mfma_f32_32x32x16_bf16 v[96:111], v[150:153], v[130:133], v[96:111]
	ds_read_b128 v[146:149], v193 offset:16384
	ds_read_b128 v[150:153], v193 offset:24576
	ds_read_b64_tr_b16 v[184:185], v206 offset:0
	ds_read_b64_tr_b16 v[186:187], v206 offset:0x800
	ds_read_b64_tr_b16 v[216:217], v206 offset:0x1000
	ds_read_b64_tr_b16 v[218:219], v206 offset:0x1800
	ds_read_b64_tr_b16 v[220:221], v206 offset:0x2000
	ds_read_b64_tr_b16 v[222:223], v206 offset:0x2800
	ds_read_b64_tr_b16 v[224:225], v206 offset:0x3000
	ds_read_b64_tr_b16 v[226:227], v206 offset:0x3800
	v_permlane32_swap_b32_e32 v69, v71
	v_permlane32_swap_b32_e32 v72, v74
	v_permlane32_swap_b32_e32 v73, v75
	v_permlane32_swap_b32_e32 v76, v78
	v_permlane32_swap_b32_e32 v77, v79
	v_permlane32_swap_b32_e32 v180, v182
	s_waitcnt lgkmcnt(9)
	v_mfma_f32_32x32x16_bf16 v[80:95], v[146:149], v[134:137], v[80:95]
	s_waitcnt lgkmcnt(8)
	v_mfma_f32_32x32x16_bf16 v[96:111], v[150:153], v[134:137], v[96:111]
	s_waitcnt vmcnt(0)
	ds_write_b128 v211, v[162:165] offset:32768
	s_nop 0
	s_waitcnt lgkmcnt(7)
	v_mfma_f32_32x32x16_bf16 v[0:15], v[64:67], v[184:187], v[0:15]
	ds_read_b64_tr_b16 v[184:185], v206 offset:0x200
	ds_read_b64_tr_b16 v[186:187], v206 offset:0xa00
	v_add_co_u32_e32 v150, vcc, s25, v178
	s_nop 1
	v_addc_co_u32_e32 v151, vcc, -1, v179, vcc
	v_add_co_u32_e32 v154, vcc, s45, v178
	s_nop 1
	v_addc_co_u32_e32 v155, vcc, -1, v179, vcc
	s_waitcnt lgkmcnt(7)
	v_mfma_f32_32x32x16_bf16 v[0:15], v[68:71], v[216:219], v[0:15]
	ds_read_b64_tr_b16 v[216:217], v206 offset:0x1200
	ds_read_b64_tr_b16 v[218:219], v206 offset:0x1a00
	global_load_dwordx4 v[146:149], v[150:151], off
	s_nop 0
	global_load_dwordx4 v[150:153], v[150:151], off offset:-512
	s_nop 0
	global_load_dwordx4 v[158:161], v[154:155], off
	s_nop 0
	global_load_dwordx4 v[154:157], v[154:155], off offset:-512
	s_waitcnt lgkmcnt(7)
	v_mfma_f32_32x32x16_bf16 v[0:15], v[72:75], v[220:223], v[0:15]
	ds_read_b64_tr_b16 v[220:221], v206 offset:0x2200
	ds_read_b64_tr_b16 v[222:223], v206 offset:0x2a00
	s_waitcnt lgkmcnt(7)
	v_mfma_f32_32x32x16_bf16 v[0:15], v[76:79], v[224:227], v[0:15]
	ds_read_b64_tr_b16 v[224:225], v206 offset:0x3200
	ds_read_b64_tr_b16 v[226:227], v206 offset:0x3a00
	ds_write_b128 v212, v[174:177] offset:32768
	s_waitcnt lgkmcnt(7)
	v_mfma_f32_32x32x16_bf16 v[16:31], v[64:67], v[184:187], v[16:31]
	ds_read_b64_tr_b16 v[184:185], v206 offset:0x400
	ds_read_b64_tr_b16 v[186:187], v206 offset:0xc00
	s_waitcnt lgkmcnt(7)
	v_mfma_f32_32x32x16_bf16 v[16:31], v[68:71], v[216:219], v[16:31]
	ds_read_b64_tr_b16 v[216:217], v206 offset:0x1400
	ds_read_b64_tr_b16 v[218:219], v206 offset:0x1c00
	s_waitcnt lgkmcnt(7)
	v_mfma_f32_32x32x16_bf16 v[16:31], v[72:75], v[220:223], v[16:31]
	ds_read_b64_tr_b16 v[220:221], v206 offset:0x2400
	ds_read_b64_tr_b16 v[222:223], v206 offset:0x2c00
	s_waitcnt lgkmcnt(7)
	v_mfma_f32_32x32x16_bf16 v[16:31], v[76:79], v[224:227], v[16:31]
	ds_read_b64_tr_b16 v[224:225], v206 offset:0x3400
	ds_read_b64_tr_b16 v[226:227], v206 offset:0x3c00
	ds_write_b128 v213, v[166:169] offset:32768
	s_waitcnt lgkmcnt(7)
	v_mfma_f32_32x32x16_bf16 v[32:47], v[64:67], v[184:187], v[32:47]
	ds_read_b64_tr_b16 v[184:185], v206 offset:0x600
	ds_read_b64_tr_b16 v[186:187], v206 offset:0xe00
	v_exp_f32_e32 v215, v90
	v_exp_f32_e32 v188, v84
	s_waitcnt lgkmcnt(7)
	v_mfma_f32_32x32x16_bf16 v[32:47], v[68:71], v[216:219], v[32:47]
	ds_read_b64_tr_b16 v[216:217], v206 offset:0x1600
	ds_read_b64_tr_b16 v[218:219], v206 offset:0x1e00
	v_exp_f32_e32 v189, v85
	v_exp_f32_e32 v196, v86
	s_waitcnt lgkmcnt(7)
	v_mfma_f32_32x32x16_bf16 v[32:47], v[72:75], v[220:223], v[32:47]
	ds_read_b64_tr_b16 v[220:221], v206 offset:0x2600
	ds_read_b64_tr_b16 v[222:223], v206 offset:0x2e00
	v_exp_f32_e32 v197, v87
	v_exp_f32_e32 v198, v88
	s_waitcnt lgkmcnt(7)
	v_mfma_f32_32x32x16_bf16 v[32:47], v[76:79], v[224:227], v[32:47]
	ds_read_b64_tr_b16 v[224:225], v206 offset:0x3600
	ds_read_b64_tr_b16 v[226:227], v206 offset:0x3e00
	v_exp_f32_e32 v199, v89
	ds_write_b128 v214, v[170:173] offset:32768
	s_waitcnt lgkmcnt(7)
	v_mfma_f32_32x32x16_bf16 v[48:63], v[64:67], v[184:187], v[48:63]
	s_waitcnt vmcnt(4)
	v_exp_f32_e32 v184, v80
	v_exp_f32_e32 v185, v81
	v_exp_f32_e32 v186, v82
	v_exp_f32_e32 v187, v83
	s_waitcnt lgkmcnt(5)
	v_mfma_f32_32x32x16_bf16 v[48:63], v[68:71], v[216:219], v[48:63]
	v_exp_f32_e32 v219, v94
	v_exp_f32_e32 v216, v91
	s_waitcnt lgkmcnt(3)
	v_mfma_f32_32x32x16_bf16 v[48:63], v[72:75], v[220:223], v[48:63]
	v_exp_f32_e32 v220, v95
	v_exp_f32_e32 v217, v92
	v_exp_f32_e32 v218, v93
	s_waitcnt lgkmcnt(0)
	s_barrier
; __device__ __forceinline__ void finishSM(f32x16& p0, f32x16& p1, float alpha, float& l_reg, bf16x8& pa0, bf16x8& pa1, bf16x8& pa2, bf16x8& pa3) {
;   for (int r = 0; r < 16; ++r) p1[r] = __builtin_amdgcn_exp2f(p1[r]);
;   float ps = 0; for (int r = 0; r < 16; ++r) ps += p0[r]; for (int r = 0; r < 16; ++r) ps += p1[r];
;   { auto rr = __builtin_amdgcn_permlane32_swap(__float_as_uint(ps), __float_as_uint(ps), false, false);
;     ps = __uint_as_float(rr[0]) + __uint_as_float(rr[1]); }
;   l_reg = l_reg * alpha + ps;
;     ...
;   PK4(p0, 0, pa0); PK4(p0, 8, pa1); PK4(p1, 0, pa2); PK4(p1, 8, pa3);
;     ...
; }
	v_mfma_f32_32x32x16_bf16 v[48:63], v[76:79], v[224:227], v[48:63]
	ds_read_b128 v[64:67], v207 offset:32768
	ds_read_b128 v[80:83], v207 offset:40960
	ds_read_b128 v[162:165], v208 offset:32768
	ds_read_b128 v[166:169], v208 offset:40960
	v_exp_f32_e32 v170, v104
	v_exp_f32_e32 v171, v105
	v_exp_f32_e32 v172, v106
	v_exp_f32_e32 v173, v107
	v_exp_f32_e32 v174, v108
	v_exp_f32_e32 v175, v109
	v_exp_f32_e32 v176, v110
	v_exp_f32_e32 v111, v111
	s_waitcnt lgkmcnt(3)
	v_mfma_f32_32x32x16_bf16 v[64:79], v[64:67], v[142:145], 0
	v_exp_f32_e32 v236, v96
	v_add_f32_e32 v96, 0, v184
	v_add_f32_e32 v96, v185, v96
	v_add_f32_e32 v96, v186, v96
	s_waitcnt lgkmcnt(2)
	v_mfma_f32_32x32x16_bf16 v[80:95], v[80:83], v[142:145], 0
	v_add_f32_e32 v96, v187, v96
	v_add_f32_e32 v96, v188, v96
	v_add_f32_e32 v96, v189, v96
	s_waitcnt lgkmcnt(1)
	v_mfma_f32_32x32x16_bf16 v[64:79], v[162:165], v[138:141], v[64:79]
	v_add_f32_e32 v96, v196, v96
	v_add_f32_e32 v96, v197, v96
	v_add_f32_e32 v96, v198, v96
	s_waitcnt lgkmcnt(0)
	v_mfma_f32_32x32x16_bf16 v[80:95], v[166:169], v[138:141], v[80:95]
	ds_read_b128 v[162:165], v209 offset:32768
	ds_read_b128 v[166:169], v209 offset:40960
	v_add_f32_e32 v96, v199, v96
	v_add_f32_e32 v96, v215, v96
	v_add_f32_e32 v96, v216, v96
	v_add_f32_e32 v96, v217, v96
	v_exp_f32_e32 v237, v97
	s_waitcnt lgkmcnt(1)
	v_mfma_f32_32x32x16_bf16 v[64:79], v[162:165], v[112:115], v[64:79]
	v_add_f32_e32 v96, v218, v96
	v_exp_f32_e32 v238, v98
	v_add_f32_e32 v96, v219, v96
	v_exp_f32_e32 v239, v99
	s_waitcnt lgkmcnt(0)
	v_mfma_f32_32x32x16_bf16 v[80:95], v[166:169], v[112:115], v[80:95]
	ds_read_b128 v[162:165], v210 offset:32768
	ds_read_b128 v[166:169], v210 offset:40960
	v_add_f32_e32 v96, v220, v96
	v_exp_f32_e32 v247, v100
	v_add_f32_e32 v96, v236, v96
	v_exp_f32_e32 v248, v101
	s_waitcnt lgkmcnt(1)
	v_mfma_f32_32x32x16_bf16 v[64:79], v[162:165], v[116:119], v[64:79]
	v_add_f32_e32 v96, v237, v96
	v_exp_f32_e32 v249, v102
	v_add_f32_e32 v96, v238, v96
	v_exp_f32_e32 v252, v103
	s_waitcnt lgkmcnt(0)
	v_mfma_f32_32x32x16_bf16 v[80:95], v[166:169], v[116:119], v[80:95]
	ds_read_b128 v[162:165], v190 offset:32768
	ds_read_b128 v[166:169], v190 offset:40960
	v_add_f32_e32 v96, v239, v96
	v_add_f32_e32 v96, v247, v96
	v_add_f32_e32 v96, v248, v96
	v_add_f32_e32 v96, v249, v96
	v_add_f32_e32 v96, v252, v96
	v_add_f32_e32 v96, v170, v96
	s_waitcnt lgkmcnt(1)
	v_mfma_f32_32x32x16_bf16 v[64:79], v[162:165], v[120:123], v[64:79]
	v_add_f32_e32 v96, v171, v96
	v_add_f32_e32 v96, v172, v96
	v_add_f32_e32 v96, v173, v96
	v_add_f32_e32 v96, v174, v96
	v_add_f32_e32 v96, v175, v96
	s_waitcnt lgkmcnt(0)
	v_mfma_f32_32x32x16_bf16 v[80:95], v[166:169], v[120:123], v[80:95]
	ds_read_b128 v[162:165], v191 offset:32768
	ds_read_b128 v[166:169], v191 offset:40960
	v_add_f32_e32 v96, v176, v96
	v_add_f32_e32 v181, v111, v96
	v_mov_b32_e32 v183, v181
	s_nop 1
	v_permlane32_swap_b32_e32 v181, v183
	v_add_f32_e32 v96, v180, v182
	v_add_f32_e32 v97, v181, v183
	s_waitcnt lgkmcnt(1)
	v_mfma_f32_32x32x16_bf16 v[64:79], v[162:165], v[124:127], v[64:79]
	s_nop 0
	v_add_f32_e32 v96, v128, v96
	v_add_f32_e32 v128, v96, v97
	v_cvt_pk_bf16_f32 v96, v184, v185
	v_cvt_pk_bf16_f32 v97, v186, v187
	s_waitcnt lgkmcnt(0)
	v_mfma_f32_32x32x16_bf16 v[80:95], v[166:169], v[124:127], v[80:95]
	ds_read_b128 v[162:165], v192 offset:32768
	ds_read_b128 v[166:169], v192 offset:40960
	v_cvt_pk_bf16_f32 v98, v188, v189
	v_cvt_pk_bf16_f32 v99, v196, v197
	v_cvt_pk_bf16_f32 v100, v198, v199
	v_cvt_pk_bf16_f32 v101, v215, v216
	v_cvt_pk_bf16_f32 v102, v217, v218
	v_cvt_pk_bf16_f32 v103, v219, v220
	s_waitcnt lgkmcnt(1)
	v_mfma_f32_32x32x16_bf16 v[64:79], v[162:165], v[130:133], v[64:79]
	v_cvt_pk_bf16_f32 v104, v236, v237
	v_cvt_pk_bf16_f32 v105, v238, v239
	v_cvt_pk_bf16_f32 v106, v247, v248
	v_cvt_pk_bf16_f32 v107, v249, v252
	v_cvt_pk_bf16_f32 v108, v170, v171
	s_waitcnt lgkmcnt(0)
	v_mfma_f32_32x32x16_bf16 v[80:95], v[166:169], v[130:133], v[80:95]
	ds_read_b128 v[162:165], v193 offset:32768
	ds_read_b128 v[166:169], v193 offset:40960
	ds_read_b64_tr_b16 v[180:181], v206 offset:0x4000
	ds_read_b64_tr_b16 v[182:183], v206 offset:0x4800
	ds_read_b64_tr_b16 v[184:185], v206 offset:0x5000
	ds_read_b64_tr_b16 v[186:187], v206 offset:0x5800
	ds_read_b64_tr_b16 v[216:217], v206 offset:0x6000
	ds_read_b64_tr_b16 v[218:219], v206 offset:0x6800
	ds_read_b64_tr_b16 v[220:221], v206 offset:0x7000
	ds_read_b64_tr_b16 v[222:223], v206 offset:0x7800
	v_cvt_pk_bf16_f32 v109, v172, v173
	v_cvt_pk_bf16_f32 v110, v174, v175
	v_cvt_pk_bf16_f32 v111, v176, v111
	s_nop 0
	v_permlane32_swap_b32_e32 v96, v98
	v_permlane32_swap_b32_e32 v97, v99
	s_waitcnt lgkmcnt(9)
	v_mfma_f32_32x32x16_bf16 v[64:79], v[162:165], v[134:137], v[64:79]
	v_permlane32_swap_b32_e32 v100, v102
	v_permlane32_swap_b32_e32 v101, v103
	v_permlane32_swap_b32_e32 v104, v106
	v_permlane32_swap_b32_e32 v105, v107
	v_permlane32_swap_b32_e32 v108, v110
	s_waitcnt lgkmcnt(8)
	v_mfma_f32_32x32x16_bf16 v[80:95], v[166:169], v[134:137], v[80:95]
	v_permlane32_swap_b32_e32 v109, v111
	s_waitcnt vmcnt(0)
	ds_write_b128 v211, v[146:149]
	s_nop 0
	s_waitcnt lgkmcnt(7)
	v_mfma_f32_32x32x16_bf16 v[0:15], v[96:99], v[180:183], v[0:15]
	ds_read_b64_tr_b16 v[180:181], v206 offset:0x4200
	ds_read_b64_tr_b16 v[182:183], v206 offset:0x4a00
	v_add_co_u32_e32 v166, vcc, s52, v178
	s_nop 1
	v_addc_co_u32_e32 v167, vcc, -1, v179, vcc
	v_add_co_u32_e32 v170, vcc, s53, v178
	s_nop 1
	v_addc_co_u32_e32 v171, vcc, -1, v179, vcc
	s_waitcnt lgkmcnt(7)
; #define SBAR() __builtin_amdgcn_sched_barrier(0)
; template <int D0, int BOFF> __device__ __forceinline__ void pv_one_i(f32x16& od, int vb, bf16x8 pa0, bf16x8 pa1, bf16x8 pa2, bf16x8 pa3) {
;   const s16x4 l0 = tr_read<BOFF + v_rd_off(D0, 0, 0)>(vb), h0 = tr_read<BOFF + v_rd_off(D0, 0, 1)>(vb), l1 = tr_read<BOFF + v_rd_off(D0, 1, 0)>(vb), h1 = tr_read<BOFF + v_rd_off(D0, 1, 1)>(vb);
;   const s16x4 l2 = tr_read<BOFF + v_rd_off(D0, 2, 0)>(vb), h2 = tr_read<BOFF + v_rd_off(D0, 2, 1)>(vb), l3 = tr_read<BOFF + v_rd_off(D0, 3, 0)>(vb), h3 = tr_read<BOFF + v_rd_off(D0, 3, 1)>(vb);
;   asm volatile("s_waitcnt lgkmcnt(0)" ::: "memory"); SBAR();
;     ...
;   od = __builtin_amdgcn_mfma_f32_32x32x16_bf16(pa0, PK(l0, h0), od, 0, 0, 0);
;   od = __builtin_amdgcn_mfma_f32_32x32x16_bf16(pa1, PK(l1, h1), od, 0, 0, 0);
;   od = __builtin_amdgcn_mfma_f32_32x32x16_bf16(pa2, PK(l2, h2), od, 0, 0, 0);
;   od = __builtin_amdgcn_mfma_f32_32x32x16_bf16(pa3, PK(l3, h3), od, 0, 0, 0);
;     ...
; }
; template <int BOFF> __device__ __forceinline__ void pv_i(f32x16* o, int vb, bf16x8 pa0, bf16x8 pa1, bf16x8 pa2, bf16x8 pa3) {
;   pv_one_i<0, BOFF>(o[0], vb, pa0, pa1, pa2, pa3); pv_one_i<1, BOFF>(o[1], vb, pa0, pa1, pa2, pa3); pv_one_i<2, BOFF>(o[2], vb, pa0, pa1, pa2, pa3); pv_one_i<3, BOFF>(o[3], vb, pa0, pa1, pa2, pa3);
; }
	v_mfma_f32_32x32x16_bf16 v[0:15], v[100:103], v[184:187], v[0:15]
	ds_read_b64_tr_b16 v[184:185], v206 offset:0x5200
	ds_read_b64_tr_b16 v[186:187], v206 offset:0x5a00
	global_load_dwordx4 v[162:165], v[166:167], off
	s_nop 0
	global_load_dwordx4 v[166:169], v[166:167], off offset:-512
	s_nop 0
	global_load_dwordx4 v[174:177], v[170:171], off
	s_nop 0
	global_load_dwordx4 v[170:173], v[170:171], off offset:-512
	s_waitcnt lgkmcnt(7)
	v_mfma_f32_32x32x16_bf16 v[0:15], v[104:107], v[216:219], v[0:15]
	ds_read_b64_tr_b16 v[216:217], v206 offset:0x6200
	ds_read_b64_tr_b16 v[218:219], v206 offset:0x6a00
	s_waitcnt lgkmcnt(7)
	v_mfma_f32_32x32x16_bf16 v[0:15], v[108:111], v[220:223], v[0:15]
	ds_read_b64_tr_b16 v[220:221], v206 offset:0x7200
	ds_read_b64_tr_b16 v[222:223], v206 offset:0x7a00
	ds_write_b128 v212, v[158:161]
	s_waitcnt lgkmcnt(7)
	v_mfma_f32_32x32x16_bf16 v[16:31], v[96:99], v[180:183], v[16:31]
	ds_read_b64_tr_b16 v[180:181], v206 offset:0x4400
	ds_read_b64_tr_b16 v[182:183], v206 offset:0x4c00
	s_waitcnt lgkmcnt(7)
	v_mfma_f32_32x32x16_bf16 v[16:31], v[100:103], v[184:187], v[16:31]
	ds_read_b64_tr_b16 v[184:185], v206 offset:0x5400
	ds_read_b64_tr_b16 v[186:187], v206 offset:0x5c00
	s_waitcnt lgkmcnt(7)
	v_mfma_f32_32x32x16_bf16 v[16:31], v[104:107], v[216:219], v[16:31]
	ds_read_b64_tr_b16 v[216:217], v206 offset:0x6400
	ds_read_b64_tr_b16 v[218:219], v206 offset:0x6c00
	s_waitcnt lgkmcnt(7)
	v_mfma_f32_32x32x16_bf16 v[16:31], v[108:111], v[220:223], v[16:31]
	ds_read_b64_tr_b16 v[220:221], v206 offset:0x7400
	ds_read_b64_tr_b16 v[222:223], v206 offset:0x7c00
	ds_write_b128 v213, v[150:153]
	s_waitcnt lgkmcnt(7)
	v_mfma_f32_32x32x16_bf16 v[32:47], v[96:99], v[180:183], v[32:47]
	ds_read_b64_tr_b16 v[180:181], v206 offset:0x4600
	ds_read_b64_tr_b16 v[182:183], v206 offset:0x4e00
	v_exp_f32_e32 v188, v72
	v_exp_f32_e32 v189, v73
	s_waitcnt lgkmcnt(7)
	v_mfma_f32_32x32x16_bf16 v[32:47], v[100:103], v[184:187], v[32:47]
	ds_read_b64_tr_b16 v[184:185], v206 offset:0x5600
	ds_read_b64_tr_b16 v[186:187], v206 offset:0x5e00
	v_exp_f32_e32 v196, v74
	v_exp_f32_e32 v197, v75
	s_waitcnt lgkmcnt(7)
	v_mfma_f32_32x32x16_bf16 v[32:47], v[104:107], v[216:219], v[32:47]
	ds_read_b64_tr_b16 v[216:217], v206 offset:0x6600
	ds_read_b64_tr_b16 v[218:219], v206 offset:0x6e00
	v_exp_f32_e32 v198, v76
	v_exp_f32_e32 v199, v77
	s_waitcnt lgkmcnt(7)
	v_mfma_f32_32x32x16_bf16 v[32:47], v[108:111], v[220:223], v[32:47]
	ds_read_b64_tr_b16 v[220:221], v206 offset:0x7600
	ds_read_b64_tr_b16 v[222:223], v206 offset:0x7e00
	ds_write_b128 v214, v[154:157]
	s_waitcnt lgkmcnt(7)
	v_mfma_f32_32x32x16_bf16 v[48:63], v[96:99], v[180:183], v[48:63]
	s_waitcnt vmcnt(4)
	v_exp_f32_e32 v180, v64
	v_exp_f32_e32 v181, v65
	v_exp_f32_e32 v182, v66
	v_exp_f32_e32 v183, v67
	s_waitcnt lgkmcnt(5)
	v_mfma_f32_32x32x16_bf16 v[48:63], v[100:103], v[184:187], v[48:63]
	v_exp_f32_e32 v184, v68
	v_exp_f32_e32 v185, v69
	v_exp_f32_e32 v186, v70
	v_exp_f32_e32 v187, v71
	s_waitcnt lgkmcnt(3)
	v_mfma_f32_32x32x16_bf16 v[48:63], v[104:107], v[216:219], v[48:63]
	v_exp_f32_e32 v216, v78
	v_exp_f32_e32 v217, v79
	s_waitcnt lgkmcnt(0)
	s_barrier
	v_mfma_f32_32x32x16_bf16 v[48:63], v[108:111], v[220:223], v[48:63]
	ds_read_b128 v[64:67], v207
	ds_read_b128 v[68:71], v207 offset:8192
	ds_read_b128 v[146:149], v208
	ds_read_b128 v[150:153], v208 offset:8192
	v_exp_f32_e32 v154, v88
	v_exp_f32_e32 v155, v89
	v_exp_f32_e32 v156, v90
	v_exp_f32_e32 v157, v91
	v_exp_f32_e32 v158, v92
	v_exp_f32_e32 v159, v93
	v_exp_f32_e32 v160, v94
	v_exp_f32_e32 v95, v95
	s_waitcnt lgkmcnt(3)
	v_mfma_f32_32x32x16_bf16 v[96:111], v[64:67], v[142:145], 0
	v_exp_f32_e32 v236, v80
	v_add_f32_e32 v80, 0, v180
	v_add_f32_e32 v80, v181, v80
	v_add_f32_e32 v80, v182, v80
	s_waitcnt lgkmcnt(2)
	v_mfma_f32_32x32x16_bf16 v[64:79], v[68:71], v[142:145], 0
	v_add_f32_e32 v80, v183, v80
	v_add_f32_e32 v80, v184, v80
	v_add_f32_e32 v80, v185, v80
	s_waitcnt lgkmcnt(1)
	v_mfma_f32_32x32x16_bf16 v[96:111], v[146:149], v[138:141], v[96:111]
	v_add_f32_e32 v80, v186, v80
	v_add_f32_e32 v80, v187, v80
	v_add_f32_e32 v80, v188, v80
	s_waitcnt lgkmcnt(0)
	v_mfma_f32_32x32x16_bf16 v[64:79], v[150:153], v[138:141], v[64:79]
	ds_read_b128 v[146:149], v209
	ds_read_b128 v[150:153], v209 offset:8192
	v_add_f32_e32 v80, v189, v80
	v_add_f32_e32 v80, v196, v80
	v_add_f32_e32 v80, v197, v80
	v_add_f32_e32 v80, v198, v80
	v_exp_f32_e32 v237, v81
	s_waitcnt lgkmcnt(1)
	v_mfma_f32_32x32x16_bf16 v[96:111], v[146:149], v[112:115], v[96:111]
	v_add_f32_e32 v80, v199, v80
	v_exp_f32_e32 v238, v82
	v_add_f32_e32 v80, v216, v80
	v_exp_f32_e32 v239, v83
	s_waitcnt lgkmcnt(0)
	v_mfma_f32_32x32x16_bf16 v[64:79], v[150:153], v[112:115], v[64:79]
	ds_read_b128 v[146:149], v210
	ds_read_b128 v[150:153], v210 offset:8192
	v_add_f32_e32 v80, v217, v80
	v_exp_f32_e32 v247, v84
	v_add_f32_e32 v80, v236, v80
	v_exp_f32_e32 v248, v85
	s_waitcnt lgkmcnt(1)
	v_mfma_f32_32x32x16_bf16 v[96:111], v[146:149], v[116:119], v[96:111]
	v_add_f32_e32 v80, v237, v80
	v_exp_f32_e32 v249, v86
	v_add_f32_e32 v80, v238, v80
	v_exp_f32_e32 v252, v87
	s_waitcnt lgkmcnt(0)
	v_mfma_f32_32x32x16_bf16 v[64:79], v[150:153], v[116:119], v[64:79]
	ds_read_b128 v[146:149], v190 offset:0
	ds_read_b128 v[150:153], v190 offset:8192
	v_add_f32_e32 v80, v239, v80
	v_add_f32_e32 v80, v247, v80
	v_add_f32_e32 v80, v248, v80
	v_add_f32_e32 v80, v249, v80
	v_add_f32_e32 v80, v252, v80
	v_add_f32_e32 v80, v154, v80
	s_waitcnt lgkmcnt(1)
	v_mfma_f32_32x32x16_bf16 v[96:111], v[146:149], v[120:123], v[96:111]
	v_add_f32_e32 v80, v155, v80
	v_add_f32_e32 v80, v156, v80
	v_add_f32_e32 v80, v157, v80
	v_add_f32_e32 v80, v158, v80
	v_add_f32_e32 v80, v159, v80
	s_waitcnt lgkmcnt(0)
; #define SLOAD(i, k0) do { sr_[i].vs0 = ld8(&Vh[(long)((k0) + sr) * LDK + sc]); sr_[i].vs1 = ld8(&Vh[(long)((k0) + 32 + sr) * LDK + sc]); \
;     sr_[i].ks0 = ld8(&Kh[(long)((k0) + sr) * LDK + sc]); sr_[i].ks1 = ld8(&Kh[(long)((k0) + 32 + sr) * LDK + sc]); } while (0)
; #define SWAIT() asm volatile("s_waitcnt vmcnt(4)" ::: "memory")
; #define SWRITE_I(B, i) do { LDSV(wv0 + (B) * 16384) = sr_[i].vs0; LDSV(wv1 + (B) * 16384) = sr_[i].vs1; LDSV(wk0 + (B) * 16384) = sr_[i].ks0; LDSV(wk1 + (B) * 16384) = sr_[i].ks1; } while (0)
; #define NOP_() do { } while (0)
; template <bool PARTIAL, bool FIXED> ...
;     ...
;   int j = 1;
;   for (; j + 6 < NT; j += 6) {
;     HALF_B(1, 0, SLOAD(1, (j + 2) * KVBLK), do { SWAIT(); SWRITE_I(2, 0); } while (0));
;     HALF_A(2, 1, NOP_(), SLOAD(0, (j + 3) * KVBLK), do { SWAIT(); SWRITE_I(0, 1); } while (0));
;     HALF_B(0, 2, SLOAD(1, (j + 4) * KVBLK), do { SWAIT(); SWRITE_I(1, 0); } while (0));
;     HALF_A(1, 0, NOP_(), SLOAD(0, (j + 5) * KVBLK), do { SWAIT(); SWRITE_I(2, 1); } while (0));
;     HALF_B(2, 1, SLOAD(1, (j + 6) * KVBLK), do { SWAIT(); SWRITE_I(0, 0); } while (0));
;     HALF_A(0, 2, NOP_(), SLOAD(0, (j + 7) * KVBLK), do { SWAIT(); SWRITE_I(1, 1); } while (0));
;   }
	v_mfma_f32_32x32x16_bf16 v[64:79], v[150:153], v[120:123], v[64:79]
	ds_read_b128 v[146:149], v191 offset:0
	ds_read_b128 v[150:153], v191 offset:8192
	v_add_f32_e32 v80, v160, v80
	v_add_f32_e32 v80, v95, v80
	v_mov_b32_e32 v81, v80
	s_nop 1
	v_permlane32_swap_b32_e32 v80, v81
	v_add_f32_e32 v80, v80, v81
	s_waitcnt lgkmcnt(1)
	v_mfma_f32_32x32x16_bf16 v[96:111], v[146:149], v[124:127], v[96:111]
	v_add_f32_e32 v215, v128, v80
	v_cvt_pk_bf16_f32 v80, v180, v181
	v_cvt_pk_bf16_f32 v81, v182, v183
	v_cvt_pk_bf16_f32 v82, v184, v185
	v_cvt_pk_bf16_f32 v83, v186, v187
	s_waitcnt lgkmcnt(0)
	v_mfma_f32_32x32x16_bf16 v[64:79], v[150:153], v[124:127], v[64:79]
	ds_read_b128 v[146:149], v192 offset:0
	ds_read_b128 v[150:153], v192 offset:8192
	v_cvt_pk_bf16_f32 v84, v188, v189
	v_cvt_pk_bf16_f32 v85, v196, v197
	v_cvt_pk_bf16_f32 v86, v198, v199
	v_cvt_pk_bf16_f32 v87, v216, v217
	v_cvt_pk_bf16_f32 v88, v236, v237
	v_cvt_pk_bf16_f32 v89, v238, v239
	s_waitcnt lgkmcnt(1)
	v_mfma_f32_32x32x16_bf16 v[96:111], v[146:149], v[130:133], v[96:111]
	v_cvt_pk_bf16_f32 v90, v247, v248
	v_cvt_pk_bf16_f32 v91, v249, v252
	v_cvt_pk_bf16_f32 v92, v154, v155
	v_cvt_pk_bf16_f32 v93, v156, v157
	v_cvt_pk_bf16_f32 v94, v158, v159
	s_waitcnt lgkmcnt(0)
	v_mfma_f32_32x32x16_bf16 v[64:79], v[150:153], v[130:133], v[64:79]
	ds_read_b128 v[146:149], v193 offset:0
	ds_read_b128 v[150:153], v193 offset:8192
	ds_read_b64_tr_b16 v[180:181], v206 offset:0x8000
	ds_read_b64_tr_b16 v[182:183], v206 offset:0x8800
	ds_read_b64_tr_b16 v[184:185], v206 offset:0x9000
	ds_read_b64_tr_b16 v[186:187], v206 offset:0x9800
	ds_read_b64_tr_b16 v[216:217], v206 offset:0xa000
	ds_read_b64_tr_b16 v[218:219], v206 offset:0xa800
	ds_read_b64_tr_b16 v[220:221], v206 offset:0xb000
	ds_read_b64_tr_b16 v[222:223], v206 offset:0xb800
	v_cvt_pk_bf16_f32 v95, v160, v95
	s_nop 0
	v_permlane32_swap_b32_e32 v80, v82
	v_permlane32_swap_b32_e32 v81, v83
	v_permlane32_swap_b32_e32 v84, v86
	v_permlane32_swap_b32_e32 v85, v87
	s_waitcnt lgkmcnt(9)
	v_mfma_f32_32x32x16_bf16 v[96:111], v[146:149], v[134:137], v[96:111]
	v_permlane32_swap_b32_e32 v88, v90
	v_permlane32_swap_b32_e32 v89, v91
	v_permlane32_swap_b32_e32 v92, v94
	v_permlane32_swap_b32_e32 v93, v95
	s_waitcnt lgkmcnt(8)
	v_mfma_f32_32x32x16_bf16 v[64:79], v[150:153], v[134:137], v[64:79]
	s_waitcnt vmcnt(0)
	ds_write_b128 v211, v[162:165] offset:16384
	s_nop 0
	s_waitcnt lgkmcnt(7)
	v_mfma_f32_32x32x16_bf16 v[0:15], v[80:83], v[180:183], v[0:15]
	ds_read_b64_tr_b16 v[180:181], v206 offset:0x8200
	ds_read_b64_tr_b16 v[182:183], v206 offset:0x8a00
	v_add_co_u32_e32 v150, vcc, s58, v178
	s_nop 1
	v_addc_co_u32_e32 v151, vcc, -1, v179, vcc
	s_waitcnt lgkmcnt(7)
	v_mfma_f32_32x32x16_bf16 v[0:15], v[84:87], v[184:187], v[0:15]
	ds_read_b64_tr_b16 v[184:185], v206 offset:0x9200
	ds_read_b64_tr_b16 v[186:187], v206 offset:0x9a00
	global_load_dwordx4 v[146:149], v[150:151], off
	global_load_dwordx4 v[154:157], v[150:151], off offset:-512
	s_nop 0
	global_load_dwordx4 v[150:153], v[178:179], off
	global_load_dwordx4 v[158:161], v[178:179], off offset:-512
	s_waitcnt lgkmcnt(7)
	v_mfma_f32_32x32x16_bf16 v[0:15], v[88:91], v[216:219], v[0:15]
	ds_read_b64_tr_b16 v[216:217], v206 offset:0xa200
	ds_read_b64_tr_b16 v[218:219], v206 offset:0xaa00
	s_waitcnt lgkmcnt(7)
	v_mfma_f32_32x32x16_bf16 v[0:15], v[92:95], v[220:223], v[0:15]
	ds_read_b64_tr_b16 v[220:221], v206 offset:0xb200
	ds_read_b64_tr_b16 v[222:223], v206 offset:0xba00
	ds_write_b128 v212, v[174:177] offset:16384
	s_waitcnt lgkmcnt(7)
	v_mfma_f32_32x32x16_bf16 v[16:31], v[80:83], v[180:183], v[16:31]
	ds_read_b64_tr_b16 v[180:181], v206 offset:0x8400
	ds_read_b64_tr_b16 v[182:183], v206 offset:0x8c00
	s_waitcnt lgkmcnt(7)
	v_mfma_f32_32x32x16_bf16 v[16:31], v[84:87], v[184:187], v[16:31]
	ds_read_b64_tr_b16 v[184:185], v206 offset:0x9400
	ds_read_b64_tr_b16 v[186:187], v206 offset:0x9c00
	s_waitcnt lgkmcnt(7)
	v_mfma_f32_32x32x16_bf16 v[16:31], v[88:91], v[216:219], v[16:31]
	ds_read_b64_tr_b16 v[216:217], v206 offset:0xa400
	ds_read_b64_tr_b16 v[218:219], v206 offset:0xac00
	s_waitcnt lgkmcnt(7)
	v_mfma_f32_32x32x16_bf16 v[16:31], v[92:95], v[220:223], v[16:31]
	ds_read_b64_tr_b16 v[220:221], v206 offset:0xb400
	ds_read_b64_tr_b16 v[222:223], v206 offset:0xbc00
	ds_write_b128 v213, v[166:169] offset:16384
	s_waitcnt lgkmcnt(7)
	v_mfma_f32_32x32x16_bf16 v[32:47], v[80:83], v[180:183], v[32:47]
	ds_read_b64_tr_b16 v[180:181], v206 offset:0x8600
	ds_read_b64_tr_b16 v[182:183], v206 offset:0x8e00
	v_exp_f32_e32 v229, v96
	v_exp_f32_e32 v243, v97
	s_waitcnt lgkmcnt(7)
	v_mfma_f32_32x32x16_bf16 v[32:47], v[84:87], v[184:187], v[32:47]
	ds_read_b64_tr_b16 v[184:185], v206 offset:0x9600
	ds_read_b64_tr_b16 v[186:187], v206 offset:0x9e00
	v_exp_f32_e32 v244, v98
	v_exp_f32_e32 v246, v99
	s_waitcnt lgkmcnt(7)
	v_mfma_f32_32x32x16_bf16 v[32:47], v[88:91], v[216:219], v[32:47]
	ds_read_b64_tr_b16 v[216:217], v206 offset:0xa600
	ds_read_b64_tr_b16 v[218:219], v206 offset:0xae00
	v_exp_f32_e32 v242, v100
	v_exp_f32_e32 v245, v101
	s_waitcnt lgkmcnt(7)
	v_mfma_f32_32x32x16_bf16 v[32:47], v[92:95], v[220:223], v[32:47]
	ds_read_b64_tr_b16 v[220:221], v206 offset:0xb600
	ds_read_b64_tr_b16 v[222:223], v206 offset:0xbe00
	v_exp_f32_e32 v227, v102
	v_exp_f32_e32 v228, v103
	ds_write_b128 v214, v[170:173] offset:16384
	s_waitcnt lgkmcnt(7)
	v_mfma_f32_32x32x16_bf16 v[48:63], v[80:83], v[180:183], v[48:63]
	s_waitcnt lgkmcnt(5)
	v_mfma_f32_32x32x16_bf16 v[48:63], v[84:87], v[184:187], v[48:63]
	v_exp_f32_e32 v226, v105
	v_exp_f32_e32 v224, v106
	v_exp_f32_e32 v225, v107
	s_waitcnt vmcnt(4)
	s_add_i32 s28, s28, 6
	v_lshl_add_u64 v[178:179], v[178:179], 0, s[60:61]
	s_waitcnt lgkmcnt(3)
	v_mfma_f32_32x32x16_bf16 v[48:63], v[88:91], v[216:219], v[48:63]
	v_exp_f32_e32 v219, v110
	s_cmpk_lt_u32 s28, 0x75
	s_waitcnt lgkmcnt(1)
	v_mfma_f32_32x32x16_bf16 v[48:63], v[92:95], v[220:223], v[48:63]
	v_exp_f32_e32 v223, v104
	v_exp_f32_e32 v220, v108
	v_exp_f32_e32 v222, v109
	v_exp_f32_e32 v221, v111
	s_cbranch_scc1 .LBB0_352
; __device__ __forceinline__ void finishSM(f32x16& p0, f32x16& p1, float alpha, float& l_reg, bf16x8& pa0, bf16x8& pa1, bf16x8& pa2, bf16x8& pa3) {
;   for (int r = 0; r < 16; ++r) p1[r] = __builtin_amdgcn_exp2f(p1[r]);
;   float ps = 0; for (int r = 0; r < 16; ++r) ps += p0[r]; for (int r = 0; r < 16; ++r) ps += p1[r];
;   { auto rr = __builtin_amdgcn_permlane32_swap(__float_as_uint(ps), __float_as_uint(ps), false, false);
;     ps = __uint_as_float(rr[0]) + __uint_as_float(rr[1]); }
;   l_reg = l_reg * alpha + ps;
;     ...
;   PK4(p0, 0, pa0); PK4(p0, 8, pa1); PK4(p1, 0, pa2); PK4(p1, 8, pa3);
;     ...
; }
	v_mov_b32_e32 v252, 0x7fc00000
	v_readlane_b32 s8, v255, 42
	v_readlane_b32 s9, v255, 43
	s_add_u32 s2, s8, s6
	s_addc_u32 s3, s9, s7
	s_lshl_b32 s4, s65, 1
	s_add_u32 s2, s2, s4
	s_addc_u32 s3, s3, 0
	v_ashrrev_i32_e32 v82, 1, v195
	v_mov_b64_e32 v[80:81], s[2:3]
	v_mad_i64_i32 v[80:81], s[2:3], v82, s17, v[80:81]
	v_lshlrev_b32_e32 v82, 7, v195
	v_and_b32_e32 v128, 0x80, v82
	v_lshl_add_u64 v[80:81], v[80:81], 0, v[128:129]
	s_add_u32 s4, s8, s64
	global_load_dword v216, v[80:81], off
	v_cmp_gt_i32_e32 vcc, s14, v195
	v_mov_b32_e32 v80, 0xa00
	v_mov_b32_e32 v81, 0x800
	s_addc_u32 s5, s9, s57
	v_cndmask_b32_e32 v80, v80, v81, vcc
	v_mov_b32_e32 v81, v129
	v_bfe_u32 v82, v195, 1, 7
	v_lshl_add_u64 v[80:81], s[4:5], 0, v[80:81]
	s_lshl_b32 s46, s56, 1
	v_mul_u32_u24_e32 v82, 0x600, v82
	v_lshl_add_u64 v[80:81], v[80:81], 0, s[46:47]
	v_lshlrev_b32_e32 v82, 1, v82
	v_mov_b32_e32 v83, v129
	v_lshl_add_u64 v[80:81], v[80:81], 0, v[82:83]
	v_lshl_add_u64 v[80:81], v[80:81], 0, v[128:129]
	global_load_dword v217, v[80:81], off
	v_and_b32_e32 v247, 0x3fffffc0, v195
	s_waitcnt lgkmcnt(0)
	s_barrier
	ds_read_b128 v[80:83], v207 offset:16384
	ds_read_b128 v[96:99], v207 offset:24576
	ds_read_b128 v[100:103], v208 offset:16384
	ds_read_b128 v[170:173], v208 offset:24576
	v_exp_f32_e32 v104, v68
	v_exp_f32_e32 v105, v69
	s_waitcnt lgkmcnt(3)
	v_mfma_f32_32x32x16_bf16 v[80:95], v[80:83], v[142:145], 0
	v_exp_f32_e32 v106, v70
	v_exp_f32_e32 v107, v71
	v_exp_f32_e32 v108, v72
	v_exp_f32_e32 v109, v73
	v_exp_f32_e32 v110, v74
	v_exp_f32_e32 v111, v75
	v_exp_f32_e32 v196, v76
	s_waitcnt lgkmcnt(1)
	v_mfma_f32_32x32x16_bf16 v[80:95], v[100:103], v[138:141], v[80:95]
	ds_read_b128 v[100:103], v209 offset:16384
	ds_read_b128 v[162:165], v209 offset:24576
	v_exp_f32_e32 v197, v77
	v_exp_f32_e32 v198, v78
	v_exp_f32_e32 v79, v79
	s_waitcnt lgkmcnt(1)
	v_mfma_f32_32x32x16_bf16 v[80:95], v[100:103], v[112:115], v[80:95]
	ds_read_b128 v[100:103], v210 offset:16384
	ds_read_b128 v[166:169], v210 offset:24576
	s_waitcnt lgkmcnt(1)
	v_mfma_f32_32x32x16_bf16 v[80:95], v[100:103], v[116:119], v[80:95]
	ds_read_b128 v[100:103], v190 offset:16384
	ds_read_b128 v[174:177], v190 offset:24576
	s_waitcnt lgkmcnt(1)
	v_mfma_f32_32x32x16_bf16 v[80:95], v[100:103], v[120:123], v[80:95]
	ds_read_b128 v[100:103], v191 offset:16384
	ds_read_b128 v[178:181], v191 offset:24576
	s_waitcnt lgkmcnt(1)
	v_mfma_f32_32x32x16_bf16 v[80:95], v[100:103], v[124:127], v[80:95]
	ds_read_b128 v[100:103], v192 offset:16384
	ds_read_b128 v[182:185], v192 offset:24576
	s_waitcnt lgkmcnt(1)
	v_mfma_f32_32x32x16_bf16 v[80:95], v[100:103], v[130:133], v[80:95]
	ds_read_b128 v[100:103], v193 offset:16384
	ds_read_b128 v[186:189], v193 offset:24576
	s_waitcnt lgkmcnt(1)
	v_mfma_f32_32x32x16_bf16 v[80:95], v[100:103], v[134:137], v[80:95]
	v_exp_f32_e32 v100, v64
	v_add_f32_e32 v64, 0, v229
	v_add_f32_e32 v64, v243, v64
	v_add_f32_e32 v64, v244, v64
	v_add_f32_e32 v64, v246, v64
	v_add_f32_e32 v64, v242, v64
	v_add_f32_e32 v64, v245, v64
	v_add_f32_e32 v64, v227, v64
	v_add_f32_e32 v64, v228, v64
	v_add_f32_e32 v64, v223, v64
	v_add_f32_e32 v64, v226, v64
	v_add_f32_e32 v64, v224, v64
	v_add_f32_e32 v64, v225, v64
	v_add_f32_e32 v64, v220, v64
	v_exp_f32_e32 v101, v65
	v_add_f32_e32 v64, v222, v64
	v_exp_f32_e32 v102, v66
	v_add_f32_e32 v64, v219, v64
	v_exp_f32_e32 v103, v67
	v_add_f32_e32 v64, v221, v64
	v_add_f32_e32 v64, v100, v64
	v_add_f32_e32 v64, v101, v64
	v_add_f32_e32 v64, v102, v64
	v_add_f32_e32 v64, v103, v64
	v_add_f32_e32 v64, v104, v64
	v_add_f32_e32 v64, v105, v64
	v_add_f32_e32 v64, v106, v64
	v_add_f32_e32 v64, v107, v64
	v_add_f32_e32 v64, v108, v64
	v_add_f32_e32 v64, v109, v64
	v_add_f32_e32 v64, v110, v64
	v_add_f32_e32 v64, v111, v64
	v_add_f32_e32 v64, v196, v64
	v_add_f32_e32 v64, v197, v64
	v_add_f32_e32 v64, v198, v64
	v_add_f32_e32 v128, v79, v64
	v_mov_b32_e32 v218, v128
	s_nop 1
	v_permlane32_swap_b32_e32 v128, v218
	v_cvt_pk_bf16_f32 v64, v229, v243
	v_cvt_pk_bf16_f32 v65, v244, v246
	v_cvt_pk_bf16_f32 v66, v242, v245
	v_cvt_pk_bf16_f32 v67, v227, v228
	v_cvt_pk_bf16_f32 v68, v223, v226
	v_cvt_pk_bf16_f32 v69, v224, v225
	v_cvt_pk_bf16_f32 v70, v220, v222
	v_cvt_pk_bf16_f32 v71, v219, v221
	v_cvt_pk_bf16_f32 v72, v100, v101
	v_cvt_pk_bf16_f32 v73, v102, v103
	v_cvt_pk_bf16_f32 v74, v104, v105
	v_cvt_pk_bf16_f32 v75, v106, v107
	v_cvt_pk_bf16_f32 v76, v108, v109
	v_cvt_pk_bf16_f32 v77, v110, v111
	v_cvt_pk_bf16_f32 v78, v196, v197
	v_cvt_pk_bf16_f32 v79, v198, v79
	s_nop 0
	v_permlane32_swap_b32_e32 v64, v66
	v_permlane32_swap_b32_e32 v65, v67
	v_permlane32_swap_b32_e32 v68, v70
	v_permlane32_swap_b32_e32 v69, v71
	v_permlane32_swap_b32_e32 v72, v74
	v_permlane32_swap_b32_e32 v73, v75
	v_permlane32_swap_b32_e32 v76, v78
	v_permlane32_swap_b32_e32 v77, v79
	ds_read_b64_tr_b16 v[100:101], v206 offset:0
	ds_read_b64_tr_b16 v[102:103], v206 offset:0x800
	ds_read_b64_tr_b16 v[104:105], v206 offset:0x1000
	ds_read_b64_tr_b16 v[106:107], v206 offset:0x1800
	ds_read_b64_tr_b16 v[108:109], v206 offset:0x2000
	ds_read_b64_tr_b16 v[110:111], v206 offset:0x2800
	ds_read_b64_tr_b16 v[220:221], v206 offset:0x3000
	ds_read_b64_tr_b16 v[222:223], v206 offset:0x3800
	s_waitcnt lgkmcnt(0)
	s_nop 0
	v_mfma_f32_32x32x16_bf16 v[0:15], v[64:67], v[100:103], v[0:15]
	ds_read_b64_tr_b16 v[100:101], v206 offset:0x200
	ds_read_b64_tr_b16 v[102:103], v206 offset:0xa00
	v_mfma_f32_32x32x16_bf16 v[0:15], v[68:71], v[104:107], v[0:15]
	ds_read_b64_tr_b16 v[104:105], v206 offset:0x1200
	ds_read_b64_tr_b16 v[106:107], v206 offset:0x1a00
	v_mfma_f32_32x32x16_bf16 v[0:15], v[72:75], v[108:111], v[0:15]
	ds_read_b64_tr_b16 v[108:109], v206 offset:0x2200
	ds_read_b64_tr_b16 v[110:111], v206 offset:0x2a00
	v_mfma_f32_32x32x16_bf16 v[0:15], v[76:79], v[220:223], v[0:15]
	ds_read_b64_tr_b16 v[220:221], v206 offset:0x3200
	ds_read_b64_tr_b16 v[222:223], v206 offset:0x3a00
	s_waitcnt lgkmcnt(0)
; #define SBAR() __builtin_amdgcn_sched_barrier(0)
; __device__ __forceinline__ void finishSM(f32x16& p0, f32x16& p1, float alpha, float& l_reg, bf16x8& pa0, bf16x8& pa1, bf16x8& pa2, bf16x8& pa3) {
;   for (int r = 0; r < 16; ++r) p1[r] = __builtin_amdgcn_exp2f(p1[r]);
;   float ps = 0; for (int r = 0; r < 16; ++r) ps += p0[r]; for (int r = 0; r < 16; ++r) ps += p1[r];
;   { auto rr = __builtin_amdgcn_permlane32_swap(__float_as_uint(ps), __float_as_uint(ps), false, false);
;     ps = __uint_as_float(rr[0]) + __uint_as_float(rr[1]); }
;   l_reg = l_reg * alpha + ps;
;     ...
;   PK4(p0, 0, pa0); PK4(p0, 8, pa1); PK4(p1, 0, pa2); PK4(p1, 8, pa3);
;     ...
; }
; template <int BOFF> __device__ __forceinline__ void qkt_i(f32x16& p0, f32x16& p1, const int (&kb)[4], const bf16x8* qr) {
;   p0 = f32x16{}; p1 = f32x16{};
; #pragma unroll
;   for (int d0 = 0; d0 < 8; ++d0) { const int off = BOFF + (d0 >> 2) * 128;
;     const bf16x8 b0 = LDSV(kb[d0 & 3] + off), b1 = LDSV(kb[d0 & 3] + off + 8192);
;     p0 = __builtin_amdgcn_mfma_f32_32x32x16_bf16(b0, qr[d0], p0, 0, 0, 0);
;     p1 = __builtin_amdgcn_mfma_f32_32x32x16_bf16(b1, qr[d0], p1, 0, 0, 0); }
; }
; template <int D0, int BOFF> __device__ __forceinline__ void pv_one_i(f32x16& od, int vb, bf16x8 pa0, bf16x8 pa1, bf16x8 pa2, bf16x8 pa3) {
;   const s16x4 l0 = tr_read<BOFF + v_rd_off(D0, 0, 0)>(vb), h0 = tr_read<BOFF + v_rd_off(D0, 0, 1)>(vb), l1 = tr_read<BOFF + v_rd_off(D0, 1, 0)>(vb), h1 = tr_read<BOFF + v_rd_off(D0, 1, 1)>(vb);
;   const s16x4 l2 = tr_read<BOFF + v_rd_off(D0, 2, 0)>(vb), h2 = tr_read<BOFF + v_rd_off(D0, 2, 1)>(vb), l3 = tr_read<BOFF + v_rd_off(D0, 3, 0)>(vb), h3 = tr_read<BOFF + v_rd_off(D0, 3, 1)>(vb);
;   asm volatile("s_waitcnt lgkmcnt(0)" ::: "memory"); SBAR();
;     ...
;   od = __builtin_amdgcn_mfma_f32_32x32x16_bf16(pa0, PK(l0, h0), od, 0, 0, 0);
;   od = __builtin_amdgcn_mfma_f32_32x32x16_bf16(pa1, PK(l1, h1), od, 0, 0, 0);
;   od = __builtin_amdgcn_mfma_f32_32x32x16_bf16(pa2, PK(l2, h2), od, 0, 0, 0);
;   od = __builtin_amdgcn_mfma_f32_32x32x16_bf16(pa3, PK(l3, h3), od, 0, 0, 0);
;     ...
; }
; template <int BOFF> __device__ __forceinline__ void pv_i(f32x16* o, int vb, bf16x8 pa0, bf16x8 pa1, bf16x8 pa2, bf16x8 pa3) {
;   pv_one_i<0, BOFF>(o[0], vb, pa0, pa1, pa2, pa3); pv_one_i<1, BOFF>(o[1], vb, pa0, pa1, pa2, pa3); pv_one_i<2, BOFF>(o[2], vb, pa0, pa1, pa2, pa3); pv_one_i<3, BOFF>(o[3], vb, pa0, pa1, pa2, pa3);
	v_mfma_f32_32x32x16_bf16 v[16:31], v[64:67], v[100:103], v[16:31]
	ds_read_b64_tr_b16 v[100:101], v206 offset:0x400
	ds_read_b64_tr_b16 v[102:103], v206 offset:0xc00
	v_mfma_f32_32x32x16_bf16 v[16:31], v[68:71], v[104:107], v[16:31]
	ds_read_b64_tr_b16 v[104:105], v206 offset:0x1400
	ds_read_b64_tr_b16 v[106:107], v206 offset:0x1c00
	v_mfma_f32_32x32x16_bf16 v[16:31], v[72:75], v[108:111], v[16:31]
	ds_read_b64_tr_b16 v[108:109], v206 offset:0x2400
	ds_read_b64_tr_b16 v[110:111], v206 offset:0x2c00
	v_mfma_f32_32x32x16_bf16 v[16:31], v[76:79], v[220:223], v[16:31]
	ds_read_b64_tr_b16 v[220:221], v206 offset:0x3400
	ds_read_b64_tr_b16 v[222:223], v206 offset:0x3c00
	s_waitcnt lgkmcnt(0)
	v_mfma_f32_32x32x16_bf16 v[32:47], v[64:67], v[100:103], v[32:47]
	ds_read_b64_tr_b16 v[100:101], v206 offset:0x600
	ds_read_b64_tr_b16 v[102:103], v206 offset:0xe00
	v_mfma_f32_32x32x16_bf16 v[32:47], v[68:71], v[104:107], v[32:47]
	ds_read_b64_tr_b16 v[104:105], v206 offset:0x1600
	ds_read_b64_tr_b16 v[106:107], v206 offset:0x1e00
	v_mfma_f32_32x32x16_bf16 v[32:47], v[72:75], v[108:111], v[32:47]
	ds_read_b64_tr_b16 v[108:109], v206 offset:0x2600
	ds_read_b64_tr_b16 v[110:111], v206 offset:0x2e00
	v_mfma_f32_32x32x16_bf16 v[32:47], v[76:79], v[220:223], v[32:47]
	ds_read_b64_tr_b16 v[220:221], v206 offset:0x3600
	ds_read_b64_tr_b16 v[222:223], v206 offset:0x3e00
	s_waitcnt lgkmcnt(0)
	v_mfma_f32_32x32x16_bf16 v[48:63], v[64:67], v[100:103], v[48:63]
	s_waitcnt vmcnt(5)
	ds_write_b128 v211, v[146:149] offset:32768
	s_waitcnt vmcnt(3)
	ds_write_b128 v212, v[150:153] offset:32768
	ds_write_b128 v213, v[154:157] offset:32768
	s_waitcnt vmcnt(2)
	ds_write_b128 v214, v[158:161] offset:32768
	s_waitcnt lgkmcnt(0)
	s_barrier
	v_mfma_f32_32x32x16_bf16 v[48:63], v[68:71], v[104:107], v[48:63]
	v_mfma_f32_32x32x16_bf16 v[48:63], v[72:75], v[108:111], v[48:63]
	v_mfma_f32_32x32x16_bf16 v[48:63], v[76:79], v[220:223], v[48:63]
	ds_read_b128 v[64:67], v207 offset:32768
	ds_read_b128 v[100:103], v208 offset:32768
	s_add_i32 s2, 0, 0x18000
	s_waitcnt lgkmcnt(1)
	v_mfma_f32_32x32x16_bf16 v[64:79], v[64:67], v[142:145], 0
	s_waitcnt lgkmcnt(0)
	v_mfma_f32_32x32x16_bf16 v[64:79], v[100:103], v[138:141], v[64:79]
	ds_read_b128 v[100:103], v209 offset:32768
	s_waitcnt lgkmcnt(0)
	v_mfma_f32_32x32x16_bf16 v[64:79], v[100:103], v[112:115], v[64:79]
	ds_read_b128 v[100:103], v210 offset:32768
	s_waitcnt lgkmcnt(0)
	v_mfma_f32_32x32x16_bf16 v[64:79], v[100:103], v[116:119], v[64:79]
	ds_read_b128 v[100:103], v190 offset:32768
	s_waitcnt lgkmcnt(0)
	v_mfma_f32_32x32x16_bf16 v[64:79], v[100:103], v[120:123], v[64:79]
	ds_read_b128 v[100:103], v191 offset:32768
	s_waitcnt lgkmcnt(0)
	v_mfma_f32_32x32x16_bf16 v[64:79], v[100:103], v[124:127], v[64:79]
	ds_read_b128 v[100:103], v192 offset:32768
	s_waitcnt lgkmcnt(0)
	v_mfma_f32_32x32x16_bf16 v[64:79], v[100:103], v[130:133], v[64:79]
	ds_read_b128 v[100:103], v193 offset:32768
	s_waitcnt lgkmcnt(0)
	v_and_b32_e32 v190, 63, v195
	v_lshlrev_b32_e32 v191, 4, v195
	v_and_b32_e32 v192, 31, v195
	v_bfe_u32 v193, v195, 5, 1
	v_mfma_f32_32x32x16_bf16 v[64:79], v[100:103], v[134:137], v[64:79]
	v_mfma_f32_32x32x16_bf16 v[96:111], v[96:99], v[142:145], 0
	s_nop 10
	v_exp_f32_e32 v72, v80
	v_exp_f32_e32 v80, v81
	v_exp_f32_e32 v73, v82
	v_exp_f32_e32 v81, v83
	v_exp_f32_e32 v74, v84
	v_add_f32_e32 v84, 0, v72
	v_exp_f32_e32 v82, v85
	v_mfma_f32_32x32x16_bf16 v[96:111], v[170:173], v[138:141], v[96:111]
	v_add_f32_e32 v84, v80, v84
	v_exp_f32_e32 v75, v86
	v_add_f32_e32 v84, v73, v84
	v_exp_f32_e32 v83, v87
	v_add_f32_e32 v84, v81, v84
	v_exp_f32_e32 v76, v88
	v_add_f32_e32 v84, v74, v84
	v_mfma_f32_32x32x16_bf16 v[96:111], v[162:165], v[112:115], v[96:111]
	v_exp_f32_e32 v85, v89
	v_add_f32_e32 v84, v82, v84
	v_exp_f32_e32 v77, v90
	v_add_f32_e32 v84, v75, v84
	v_exp_f32_e32 v87, v91
	v_add_f32_e32 v84, v83, v84
	v_exp_f32_e32 v78, v92
	v_mfma_f32_32x32x16_bf16 v[96:111], v[166:169], v[116:119], v[96:111]
	v_add_f32_e32 v84, v76, v84
	v_exp_f32_e32 v89, v93
	v_add_f32_e32 v84, v85, v84
	v_exp_f32_e32 v79, v94
	v_add_f32_e32 v84, v77, v84
	v_exp_f32_e32 v90, v95
	v_add_f32_e32 v84, v87, v84
	v_mfma_f32_32x32x16_bf16 v[96:111], v[174:177], v[120:123], v[96:111]
	v_add_f32_e32 v84, v78, v84
	v_add_f32_e32 v84, v89, v84
	v_add_f32_e32 v84, v79, v84
	v_add_f32_e32 v84, v90, v84
	v_lshl_add_u32 v88, v247, 2, s2
	v_cvt_pk_bf16_f32 v72, v72, v80
	v_cvt_pk_bf16_f32 v73, v73, v81
	v_mfma_f32_32x32x16_bf16 v[96:111], v[178:181], v[124:127], v[96:111]
	v_cvt_pk_bf16_f32 v74, v74, v82
	v_cvt_pk_bf16_f32 v75, v75, v83
	v_cvt_pk_bf16_f32 v76, v76, v85
	v_cvt_pk_bf16_f32 v77, v77, v87
	v_cvt_pk_bf16_f32 v78, v78, v89
	v_cvt_pk_bf16_f32 v79, v79, v90
	s_nop 0
	v_permlane32_swap_b32_e32 v72, v74
	v_mfma_f32_32x32x16_bf16 v[96:111], v[182:185], v[130:133], v[96:111]
	v_permlane32_swap_b32_e32 v73, v75
	v_permlane32_swap_b32_e32 v76, v78
	v_permlane32_swap_b32_e32 v77, v79
	v_mfma_f32_32x32x16_bf16 v[96:111], v[186:189], v[134:137], v[96:111]
	s_nop 11
	v_exp_f32_e32 v91, v96
	v_exp_f32_e32 v92, v97
	v_exp_f32_e32 v93, v98
	v_exp_f32_e32 v94, v99
	v_exp_f32_e32 v95, v100
	v_add_f32_e32 v84, v84, v91
	v_exp_f32_e32 v96, v101
	v_add_f32_e32 v84, v92, v84
	v_exp_f32_e32 v97, v102
	v_add_f32_e32 v84, v93, v84
	v_exp_f32_e32 v98, v103
	v_add_f32_e32 v84, v94, v84
	v_exp_f32_e32 v99, v104
	v_add_f32_e32 v84, v95, v84
	v_exp_f32_e32 v100, v105
	v_add_f32_e32 v84, v96, v84
	v_exp_f32_e32 v101, v106
	v_add_f32_e32 v84, v97, v84
	v_exp_f32_e32 v102, v107
	v_add_f32_e32 v84, v98, v84
	v_exp_f32_e32 v103, v108
	v_add_f32_e32 v84, v99, v84
	v_exp_f32_e32 v104, v109
	v_add_f32_e32 v84, v100, v84
	v_exp_f32_e32 v105, v110
	v_add_f32_e32 v84, v101, v84
	v_exp_f32_e32 v106, v111
	v_add_f32_e32 v84, v102, v84
	v_add_f32_e32 v84, v103, v84
	v_add_f32_e32 v84, v104, v84
	v_add_f32_e32 v84, v105, v84
	v_add_f32_e32 v84, v106, v84
	v_mov_b32_e32 v86, v84
	s_nop 1
	v_permlane32_swap_b32_e32 v84, v86
	v_cvt_pk_bf16_f32 v80, v91, v92
	v_cvt_pk_bf16_f32 v81, v93, v94
	v_cvt_pk_bf16_f32 v82, v95, v96
	v_cvt_pk_bf16_f32 v83, v97, v98
	v_cvt_pk_bf16_f32 v90, v99, v100
	v_cvt_pk_bf16_f32 v91, v101, v102
	v_cvt_pk_bf16_f32 v92, v103, v104
	v_cvt_pk_bf16_f32 v93, v105, v106
	s_nop 0
	v_permlane32_swap_b32_e32 v80, v82
	v_permlane32_swap_b32_e32 v81, v83
	v_permlane32_swap_b32_e32 v90, v92
	v_permlane32_swap_b32_e32 v91, v93
	ds_read_b64_tr_b16 v[94:95], v206 offset:0x4000
	ds_read_b64_tr_b16 v[96:97], v206 offset:0x4800
	ds_read_b64_tr_b16 v[98:99], v206 offset:0x5000
	ds_read_b64_tr_b16 v[100:101], v206 offset:0x5800
	ds_read_b64_tr_b16 v[102:103], v206 offset:0x6000
	ds_read_b64_tr_b16 v[104:105], v206 offset:0x6800
	ds_read_b64_tr_b16 v[106:107], v206 offset:0x7000
	ds_read_b64_tr_b16 v[108:109], v206 offset:0x7800
	s_waitcnt lgkmcnt(0)
; #define SBAR() __builtin_amdgcn_sched_barrier(0)
; __device__ __forceinline__ int crow(int r, int hi) { return (r & 3) + 8 * (r >> 2) + 4 * hi; }
; #define NOP_() do { } while (0)
; template <int D0, int BOFF> __device__ __forceinline__ void pv_one_i(f32x16& od, int vb, bf16x8 pa0, bf16x8 pa1, bf16x8 pa2, bf16x8 pa3) {
;   const s16x4 l0 = tr_read<BOFF + v_rd_off(D0, 0, 0)>(vb), h0 = tr_read<BOFF + v_rd_off(D0, 0, 1)>(vb), l1 = tr_read<BOFF + v_rd_off(D0, 1, 0)>(vb), h1 = tr_read<BOFF + v_rd_off(D0, 1, 1)>(vb);
;   const s16x4 l2 = tr_read<BOFF + v_rd_off(D0, 2, 0)>(vb), h2 = tr_read<BOFF + v_rd_off(D0, 2, 1)>(vb), l3 = tr_read<BOFF + v_rd_off(D0, 3, 0)>(vb), h3 = tr_read<BOFF + v_rd_off(D0, 3, 1)>(vb);
;   asm volatile("s_waitcnt lgkmcnt(0)" ::: "memory"); SBAR();
;     ...
;   od = __builtin_amdgcn_mfma_f32_32x32x16_bf16(pa0, PK(l0, h0), od, 0, 0, 0);
;   od = __builtin_amdgcn_mfma_f32_32x32x16_bf16(pa1, PK(l1, h1), od, 0, 0, 0);
;   od = __builtin_amdgcn_mfma_f32_32x32x16_bf16(pa2, PK(l2, h2), od, 0, 0, 0);
;   od = __builtin_amdgcn_mfma_f32_32x32x16_bf16(pa3, PK(l3, h3), od, 0, 0, 0);
;     ...
; }
; template <int BOFF> __device__ __forceinline__ void pv_i(f32x16* o, int vb, bf16x8 pa0, bf16x8 pa1, bf16x8 pa2, bf16x8 pa3) {
;   pv_one_i<0, BOFF>(o[0], vb, pa0, pa1, pa2, pa3); pv_one_i<1, BOFF>(o[1], vb, pa0, pa1, pa2, pa3); pv_one_i<2, BOFF>(o[2], vb, pa0, pa1, pa2, pa3); pv_one_i<3, BOFF>(o[3], vb, pa0, pa1, pa2, pa3);
; template <bool PARTIAL, bool FIXED> ...
;     ...
;   HALF_A(2, 1, do { if (mask_last) { asm volatile("; masked tail tile" ::: "memory"); const float NEG = -INFINITY; \
;       _Pragma("unroll") for (int r = 8; r < 16; ++r) pA0[r] = NEG; _Pragma("unroll") for (int r = 0; r < 16; ++r) pA1[r] = NEG; } } while (0), NOP_(), NOP_());
;     ...
;   SBAR(); finishSM(pA0, pA1, alA, l_reg, pa0, pa1, pa2, pa3); SBAR();
;   pv_i<2 * 16384>(o, vbi, pa0, pa1, pa2, pa3);
;     ...
;   if (PARTIAL) {
;     if (wid < 2) { float* po = PO + (wid * QBLK) * 128;
; #pragma unroll
;       for (int r = 0; r < 16; ++r) { const int orow = crow(r, hi);
; #pragma unroll
;         for (int d0 = 0; d0 < 4; ++d0) po[orow * 128 + d0 * 32 + r32] = o[d0][r]; }
;       if (hi == 0) { PO[8192 + (wid * QBLK + r32) * 2] = m_reg; PO[8192 + (wid * QBLK + r32) * 2 + 1] = l_reg; } }
;     __syncthreads();
;     return;
;   }
;   if (hi == 0) li_l[r32] = l_reg; asm volatile("s_waitcnt lgkmcnt(0)" ::: "memory");
	s_nop 0
	v_mfma_f32_32x32x16_bf16 v[0:15], v[72:75], v[94:97], v[0:15]
	ds_read_b64_tr_b16 v[94:95], v206 offset:0x4200
	ds_read_b64_tr_b16 v[96:97], v206 offset:0x4a00
	v_mfma_f32_32x32x16_bf16 v[0:15], v[76:79], v[98:101], v[0:15]
	ds_read_b64_tr_b16 v[98:99], v206 offset:0x5200
	ds_read_b64_tr_b16 v[100:101], v206 offset:0x5a00
	v_mfma_f32_32x32x16_bf16 v[0:15], v[80:83], v[102:105], v[0:15]
	ds_read_b64_tr_b16 v[102:103], v206 offset:0x6200
	ds_read_b64_tr_b16 v[104:105], v206 offset:0x6a00
	v_mfma_f32_32x32x16_bf16 v[0:15], v[90:93], v[106:109], v[0:15]
	ds_read_b64_tr_b16 v[106:107], v206 offset:0x7200
	ds_read_b64_tr_b16 v[108:109], v206 offset:0x7a00
	s_waitcnt lgkmcnt(0)
	v_mfma_f32_32x32x16_bf16 v[16:31], v[72:75], v[94:97], v[16:31]
	ds_read_b64_tr_b16 v[94:95], v206 offset:0x4400
	ds_read_b64_tr_b16 v[96:97], v206 offset:0x4c00
	v_mfma_f32_32x32x16_bf16 v[16:31], v[76:79], v[98:101], v[16:31]
	ds_read_b64_tr_b16 v[98:99], v206 offset:0x5400
	ds_read_b64_tr_b16 v[100:101], v206 offset:0x5c00
	v_mfma_f32_32x32x16_bf16 v[16:31], v[80:83], v[102:105], v[16:31]
	ds_read_b64_tr_b16 v[102:103], v206 offset:0x6400
	ds_read_b64_tr_b16 v[104:105], v206 offset:0x6c00
	v_mfma_f32_32x32x16_bf16 v[16:31], v[90:93], v[106:109], v[16:31]
	ds_read_b64_tr_b16 v[106:107], v206 offset:0x7400
	ds_read_b64_tr_b16 v[108:109], v206 offset:0x7c00
	s_waitcnt lgkmcnt(0)
	v_mfma_f32_32x32x16_bf16 v[32:47], v[72:75], v[94:97], v[32:47]
	ds_read_b64_tr_b16 v[94:95], v206 offset:0x4600
	ds_read_b64_tr_b16 v[96:97], v206 offset:0x4e00
	v_mfma_f32_32x32x16_bf16 v[32:47], v[76:79], v[98:101], v[32:47]
	ds_read_b64_tr_b16 v[98:99], v206 offset:0x5600
	ds_read_b64_tr_b16 v[100:101], v206 offset:0x5e00
	v_mfma_f32_32x32x16_bf16 v[32:47], v[80:83], v[102:105], v[32:47]
	ds_read_b64_tr_b16 v[102:103], v206 offset:0x6600
	ds_read_b64_tr_b16 v[104:105], v206 offset:0x6e00
	v_mfma_f32_32x32x16_bf16 v[32:47], v[90:93], v[106:109], v[32:47]
	ds_read_b64_tr_b16 v[106:107], v206 offset:0x7600
	ds_read_b64_tr_b16 v[108:109], v206 offset:0x7e00
	s_waitcnt lgkmcnt(0)
	v_mfma_f32_32x32x16_bf16 v[48:63], v[72:75], v[94:97], v[48:63]
	v_exp_f32_e32 v64, v64
	v_exp_f32_e32 v65, v65
	v_exp_f32_e32 v66, v66
	v_exp_f32_e32 v67, v67
	v_exp_f32_e32 v68, v68
	v_exp_f32_e32 v69, v69
	v_exp_f32_e32 v70, v70
	v_mfma_f32_32x32x16_bf16 v[48:63], v[76:79], v[98:101], v[48:63]
	v_exp_f32_e32 v71, v71
	v_mfma_f32_32x32x16_bf16 v[48:63], v[80:83], v[102:105], v[48:63]
	v_mfma_f32_32x32x16_bf16 v[48:63], v[90:93], v[106:109], v[48:63]
	v_add_f32_e32 v72, 0, v64
	v_add_f32_e32 v72, v65, v72
	v_add_f32_e32 v72, v66, v72
	v_add_f32_e32 v72, v67, v72
	v_add_f32_e32 v72, v68, v72
	v_add_f32_e32 v72, v69, v72
	v_add_f32_e32 v72, v70, v72
	v_add_f32_e32 v72, v71, v72
	v_add_f32_e32 v85, 0, v72
	v_mov_b32_e32 v87, v85
	s_nop 1
	v_permlane32_swap_b32_e32 v85, v87
	v_cvt_pk_bf16_f32 v64, v64, v65
	v_cvt_pk_bf16_f32 v65, v66, v67
	v_cvt_pk_bf16_f32 v66, v68, v69
	v_cvt_pk_bf16_f32 v67, v70, v71
	v_cvt_pk_bf16_f32 v68, v129, v129
	v_cvt_pk_bf16_f32 v69, v129, v129
	v_cvt_pk_bf16_f32 v70, v129, v129
	v_cvt_pk_bf16_f32 v71, v129, v129
	v_cvt_pk_bf16_f32 v72, v129, v129
	v_cvt_pk_bf16_f32 v73, v129, v129
	v_cvt_pk_bf16_f32 v74, v129, v129
	v_cvt_pk_bf16_f32 v75, v129, v129
	v_cvt_pk_bf16_f32 v76, v129, v129
	v_cvt_pk_bf16_f32 v77, v129, v129
	v_cvt_pk_bf16_f32 v78, v129, v129
	v_cvt_pk_bf16_f32 v79, v129, v129
	s_nop 0
	v_permlane32_swap_b32_e32 v64, v66
	v_permlane32_swap_b32_e32 v65, v67
	v_permlane32_swap_b32_e32 v68, v70
	v_permlane32_swap_b32_e32 v69, v71
	v_permlane32_swap_b32_e32 v72, v74
	v_permlane32_swap_b32_e32 v73, v75
	v_permlane32_swap_b32_e32 v76, v78
	v_permlane32_swap_b32_e32 v77, v79
	ds_read_b64_tr_b16 v[80:81], v206 offset:0x8000
	ds_read_b64_tr_b16 v[82:83], v206 offset:0x8800
	ds_read_b64_tr_b16 v[90:91], v206 offset:0x9000
	ds_read_b64_tr_b16 v[92:93], v206 offset:0x9800
	ds_read_b64_tr_b16 v[94:95], v206 offset:0xa000
	ds_read_b64_tr_b16 v[96:97], v206 offset:0xa800
	ds_read_b64_tr_b16 v[98:99], v206 offset:0xb000
	ds_read_b64_tr_b16 v[100:101], v206 offset:0xb800
	s_waitcnt lgkmcnt(0)
	s_nop 0
	v_mfma_f32_32x32x16_bf16 v[0:15], v[64:67], v[80:83], v[0:15]
	ds_read_b64_tr_b16 v[80:81], v206 offset:0x8200
	ds_read_b64_tr_b16 v[82:83], v206 offset:0x8a00
	v_mfma_f32_32x32x16_bf16 v[0:15], v[68:71], v[90:93], v[0:15]
	ds_read_b64_tr_b16 v[90:91], v206 offset:0x9200
	ds_read_b64_tr_b16 v[92:93], v206 offset:0x9a00
	v_mfma_f32_32x32x16_bf16 v[0:15], v[72:75], v[94:97], v[0:15]
	ds_read_b64_tr_b16 v[94:95], v206 offset:0xa200
	ds_read_b64_tr_b16 v[96:97], v206 offset:0xaa00
	v_mfma_f32_32x32x16_bf16 v[0:15], v[76:79], v[98:101], v[0:15]
	ds_read_b64_tr_b16 v[98:99], v206 offset:0xb200
	ds_read_b64_tr_b16 v[100:101], v206 offset:0xba00
	s_waitcnt lgkmcnt(0)
	v_mfma_f32_32x32x16_bf16 v[16:31], v[64:67], v[80:83], v[16:31]
	ds_read_b64_tr_b16 v[80:81], v206 offset:0x8400
	ds_read_b64_tr_b16 v[82:83], v206 offset:0x8c00
	v_mfma_f32_32x32x16_bf16 v[16:31], v[68:71], v[90:93], v[16:31]
	ds_read_b64_tr_b16 v[90:91], v206 offset:0x9400
	ds_read_b64_tr_b16 v[92:93], v206 offset:0x9c00
	v_mfma_f32_32x32x16_bf16 v[16:31], v[72:75], v[94:97], v[16:31]
	ds_read_b64_tr_b16 v[94:95], v206 offset:0xa400
	ds_read_b64_tr_b16 v[96:97], v206 offset:0xac00
	v_mfma_f32_32x32x16_bf16 v[16:31], v[76:79], v[98:101], v[16:31]
	ds_read_b64_tr_b16 v[98:99], v206 offset:0xb400
	ds_read_b64_tr_b16 v[100:101], v206 offset:0xbc00
	s_waitcnt lgkmcnt(0)
	v_mfma_f32_32x32x16_bf16 v[32:47], v[64:67], v[80:83], v[32:47]
	ds_read_b64_tr_b16 v[80:81], v206 offset:0x8600
	ds_read_b64_tr_b16 v[82:83], v206 offset:0x8e00
	v_mfma_f32_32x32x16_bf16 v[32:47], v[68:71], v[90:93], v[32:47]
	ds_read_b64_tr_b16 v[90:91], v206 offset:0x9600
	ds_read_b64_tr_b16 v[92:93], v206 offset:0x9e00
	v_mfma_f32_32x32x16_bf16 v[32:47], v[72:75], v[94:97], v[32:47]
	ds_read_b64_tr_b16 v[94:95], v206 offset:0xa600
	ds_read_b64_tr_b16 v[96:97], v206 offset:0xae00
	v_mfma_f32_32x32x16_bf16 v[32:47], v[76:79], v[98:101], v[32:47]
	ds_read_b64_tr_b16 v[98:99], v206 offset:0xb600
	ds_read_b64_tr_b16 v[100:101], v206 offset:0xbe00
	s_waitcnt lgkmcnt(0)
	v_mfma_f32_32x32x16_bf16 v[48:63], v[64:67], v[80:83], v[48:63]
	v_cmp_gt_u32_e32 vcc, 32, v190
	v_mfma_f32_32x32x16_bf16 v[48:63], v[68:71], v[90:93], v[48:63]
	v_mfma_f32_32x32x16_bf16 v[48:63], v[72:75], v[94:97], v[48:63]
	v_mfma_f32_32x32x16_bf16 v[48:63], v[76:79], v[98:101], v[48:63]
	s_and_saveexec_b64 s[28:29], vcc
	s_cbranch_execz .LBB0_309
	v_add_f32_e32 v64, v128, v218
	v_add_f32_e32 v66, v215, v64
	v_pk_add_f32 v[64:65], v[84:85], v[86:87]
	v_lshl_add_u32 v67, v192, 2, v88
	v_add_f32_e32 v64, v66, v64
	v_add_f32_e32 v64, v64, v65
	ds_write_b32 v67, v64
	s_branch .LBB0_309
